# scan finish: two dwordx4 stores (8-byte halves exchanged between lane pairs by DPP select) instead of four dwordx2
# baseline (speedup 1.0000x reference)
; __device__ __forceinline__ float row16_sum(float v) { v += dppf<0xB1>(v); v += dppf<0x4E>(v); v += dppf<0x141>(v); v += dppf<0x140>(v); return v; }
; __device__ __forceinline__ float frsq(float x) { return __builtin_amdgcn_rsqf(x); }
; __device__ __forceinline__ v2u pack4(const f32x4 v) { v2u r; r.x = pk2(v[0], v[1]); r.y = pk2(v[2], v[3]); return r; }
; __device__ __forceinline__ f32x4 unpack4(const v2u w) { f32x4 r; r[0] = bflo(w.x); r[1] = bfhi(w.x); r[2] = bflo(w.y); r[3] = bfhi(w.y); return r; }
; __device__ __forceinline__ const char* upin(const char* p) { asm volatile("" : "+s"(p)); return p; }
; __device__ __forceinline__ char* upin(char* p) { asm volatile("" : "+s"(p)); return p; }
; template <bool GDN> __device__ __forceinline__ void scan_finish(const Frame& F, int b, int h, int dir, const ScanLane& L, int s, float* PEND, const f32x4 (&Oin)[4], const ScanFin& f) {
;     const int cidx = dir ? (s < 4 ? 3 - s : 39 - s) : s; const int row0 = chunk_row0(b, cidx);
;     if (scan_first(s)) {
;         char* pp = upin((char*)PEND + (size_t)((b * 4 + h) * 36 + cidx) * 16384);
; #pragma unroll
;         for (int pr = 0; pr < 2; ++pr) { const v2u a = pack4(Oin[2 * pr]), bq = pack4(Oin[2 * pr + 1]); v4u o; o.x = a.x; o.y = a.y; o.z = bq.x; o.w = bq.y; stu<v4u>(pp + pr * 1024, L.pend, o); }
;     } else {
;         f32x4 O[4]; float ss[4] = {0.f, 0.f, 0.f, 0.f};
; #pragma unroll
;         for (int t = 0; t < 4; ++t)
;             { const f32x4 pv = unpack4(f.pend[t]);
; #pragma unroll
;             for (int i = 0; i < 4; ++i) { O[t][i] = Oin[t][i] + pv[i]; ss[i] += O[t][i] * O[t][i]; } }
; #pragma unroll
;         for (int i = 0; i < 4; ++i) ss[i] = frsq(row16_sum(ss[i]) * (1.f / 64.f) + EPS);
;         char* mp = (char*)F.MIX + ((size_t)row0 * 1024 + (GDN ? 0 : 768) + h * 64) * 2;
; #pragma unroll
;         for (int i = 0; i < 4; ++i) { const f32x4 g = unpack4(f.gz[i]); f32x4 ov;
; #pragma unroll
;             for (int t = 0; t < 4; ++t) ov[t] = O[t][i] * ss[i] * g[t];
;             stu<v2u>(upin(mp + i * 2048), L.mix, pack4(ov)); }
.LBB0_352:
	s_add_i32 s0, s25, -1
	s_cmp_eq_u32 s25, 0
	s_cselect_b64 s[10:11], -1, 0
	s_and_b64 vcc, exec, s[10:11]
	s_waitcnt lgkmcnt(0)
	s_barrier
	s_cbranch_vccnz .LBB0_357
	s_add_i32 s1, s24, 43
	s_and_b64 s[4:5], s[90:91], exec
	s_cselect_b32 s1, s0, s1
	s_cmp_lt_u32 s25, 5
	s_cselect_b32 s3, 2, 20
	s_cmp_lt_u32 s0, s3
	s_mov_b64 s[12:13], -1
	s_cbranch_scc1 .LBB0_355
	s_lshl_b32 s3, s1, 6
	s_cmp_lt_i32 s1, 4
	s_cselect_b32 s4, s63, s33
	s_add_i32 s4, s4, s3
	s_ashr_i32 s5, s4, 31
	s_lshl_b64 s[4:5], s[4:5], 11
	s_add_u32 s3, s26, s4
	s_addc_u32 s4, s27, s5
	s_add_u32 s6, s3, 0x600
	s_addc_u32 s7, s4, 0
	v_lshlrev_b32_e32 v208, 16, v12
	v_and_b32_e32 v209, 0xffff0000, v12
	v_lshlrev_b32_e32 v210, 16, v13
	v_and_b32_e32 v211, 0xffff0000, v13
	v_pk_add_f32 v[212:213], v[104:105], v[208:209]
	v_pk_add_f32 v[214:215], v[106:107], v[210:211]
	v_pk_mul_f32 v[204:205], v[212:213], v[212:213]
	v_pk_mul_f32 v[206:207], v[214:215], v[214:215]
	v_lshlrev_b32_e32 v208, 16, v14
	v_and_b32_e32 v209, 0xffff0000, v14
	v_lshlrev_b32_e32 v210, 16, v15
	v_and_b32_e32 v211, 0xffff0000, v15
	v_pk_add_f32 v[216:217], v[108:109], v[208:209]
	v_pk_add_f32 v[218:219], v[110:111], v[210:211]
	v_pk_fma_f32 v[204:205], v[216:217], v[216:217], v[204:205]
	v_pk_fma_f32 v[206:207], v[218:219], v[218:219], v[206:207]
	v_lshlrev_b32_e32 v208, 16, v16
	v_and_b32_e32 v209, 0xffff0000, v16
	v_lshlrev_b32_e32 v210, 16, v17
	v_and_b32_e32 v211, 0xffff0000, v17
	v_pk_add_f32 v[224:225], v[112:113], v[208:209]
	v_pk_add_f32 v[226:227], v[114:115], v[210:211]
	v_pk_fma_f32 v[204:205], v[224:225], v[224:225], v[204:205]
	v_pk_fma_f32 v[206:207], v[226:227], v[226:227], v[206:207]
	v_lshlrev_b32_e32 v208, 16, v18
	v_and_b32_e32 v209, 0xffff0000, v18
	v_lshlrev_b32_e32 v210, 16, v19
	v_and_b32_e32 v211, 0xffff0000, v19
	v_pk_add_f32 v[242:243], v[116:117], v[208:209]
	v_pk_add_f32 v[244:245], v[118:119], v[210:211]
	v_pk_fma_f32 v[204:205], v[242:243], v[242:243], v[204:205]
	v_pk_fma_f32 v[206:207], v[244:245], v[244:245], v[206:207]
	s_nop 1
	v_add_f32_dpp v204, v204, v204 quad_perm:[1,0,3,2] row_mask:0xf bank_mask:0xf bound_ctrl:1
	v_add_f32_dpp v205, v205, v205 quad_perm:[1,0,3,2] row_mask:0xf bank_mask:0xf bound_ctrl:1
	v_add_f32_dpp v206, v206, v206 quad_perm:[1,0,3,2] row_mask:0xf bank_mask:0xf bound_ctrl:1
	v_add_f32_dpp v207, v207, v207 quad_perm:[1,0,3,2] row_mask:0xf bank_mask:0xf bound_ctrl:1
	v_add_f32_dpp v204, v204, v204 quad_perm:[2,3,0,1] row_mask:0xf bank_mask:0xf bound_ctrl:1
	v_add_f32_dpp v205, v205, v205 quad_perm:[2,3,0,1] row_mask:0xf bank_mask:0xf bound_ctrl:1
	v_add_f32_dpp v206, v206, v206 quad_perm:[2,3,0,1] row_mask:0xf bank_mask:0xf bound_ctrl:1
	v_add_f32_dpp v207, v207, v207 quad_perm:[2,3,0,1] row_mask:0xf bank_mask:0xf bound_ctrl:1
	v_add_f32_dpp v204, v204, v204 row_half_mirror row_mask:0xf bank_mask:0xf bound_ctrl:1
	v_add_f32_dpp v205, v205, v205 row_half_mirror row_mask:0xf bank_mask:0xf bound_ctrl:1
	v_add_f32_dpp v206, v206, v206 row_half_mirror row_mask:0xf bank_mask:0xf bound_ctrl:1
	v_add_f32_dpp v207, v207, v207 row_half_mirror row_mask:0xf bank_mask:0xf bound_ctrl:1
	v_add_f32_dpp v204, v204, v204 row_mirror row_mask:0xf bank_mask:0xf bound_ctrl:1
	v_add_f32_dpp v205, v205, v205 row_mirror row_mask:0xf bank_mask:0xf bound_ctrl:1
	v_add_f32_dpp v206, v206, v206 row_mirror row_mask:0xf bank_mask:0xf bound_ctrl:1
	v_add_f32_dpp v207, v207, v207 row_mirror row_mask:0xf bank_mask:0xf bound_ctrl:1
	v_fmamk_f32 v204, v204, 0x3c800000, v231
	v_fmamk_f32 v205, v205, 0x3c800000, v231
	v_fmamk_f32 v206, v206, 0x3c800000, v231
	v_fmamk_f32 v207, v207, 0x3c800000, v231
	v_rsq_f32_e32 v204, v204
	v_rsq_f32_e32 v205, v205
	v_rsq_f32_e32 v206, v206
	v_rsq_f32_e32 v207, v207
	v_lshlrev_b32_e32 v208, 16, v130
	v_lshlrev_b32_e32 v209, 16, v132
	v_lshlrev_b32_e32 v210, 16, v134
	v_lshlrev_b32_e32 v211, 16, v136
	v_pk_mul_f32 v[212:213], v[212:213], v[204:205]
	v_pk_mul_f32 v[214:215], v[214:215], v[206:207]
	v_pk_mul_f32 v[212:213], v[212:213], v[208:209]
	v_pk_mul_f32 v[214:215], v[214:215], v[210:211]
	v_and_b32_e32 v208, 0xffff0000, v130
	v_and_b32_e32 v209, 0xffff0000, v132
	v_and_b32_e32 v210, 0xffff0000, v134
	v_and_b32_e32 v211, 0xffff0000, v136
	v_pk_mul_f32 v[216:217], v[216:217], v[204:205]
	v_pk_mul_f32 v[218:219], v[218:219], v[206:207]
	v_pk_mul_f32 v[216:217], v[216:217], v[208:209]
	v_pk_mul_f32 v[218:219], v[218:219], v[210:211]
	v_lshlrev_b32_e32 v208, 16, v131
	v_lshlrev_b32_e32 v209, 16, v133
	v_lshlrev_b32_e32 v210, 16, v135
	v_lshlrev_b32_e32 v211, 16, v137
	v_pk_mul_f32 v[224:225], v[224:225], v[204:205]
	v_pk_mul_f32 v[226:227], v[226:227], v[206:207]
	v_pk_mul_f32 v[224:225], v[224:225], v[208:209]
	v_pk_mul_f32 v[226:227], v[226:227], v[210:211]
	v_and_b32_e32 v208, 0xffff0000, v131
	v_and_b32_e32 v209, 0xffff0000, v133
	v_and_b32_e32 v210, 0xffff0000, v135
	v_and_b32_e32 v211, 0xffff0000, v137
	v_pk_mul_f32 v[242:243], v[242:243], v[204:205]
	v_pk_mul_f32 v[244:245], v[244:245], v[206:207]
	v_pk_mul_f32 v[242:243], v[242:243], v[208:209]
	v_pk_mul_f32 v[244:245], v[244:245], v[210:211]
	v_cvt_pk_bf16_f32 v204, v212, v216
	v_cvt_pk_bf16_f32 v205, v224, v242
	v_cvt_pk_bf16_f32 v210, v213, v217
	v_cvt_pk_bf16_f32 v211, v225, v243
	v_cvt_pk_bf16_f32 v206, v214, v218
	v_cvt_pk_bf16_f32 v207, v226, v244
	v_cvt_pk_bf16_f32 v218, v215, v219
	v_cvt_pk_bf16_f32 v219, v227, v245
	v_and_b32_e32 v220, 1, v232
	v_mul_u32_u24_e32 v220, 0x7f8, v220
	v_add_u32_e32 v220, v189, v220
	s_mov_b32 vcc_lo, 0x55555555
	s_mov_b32 vcc_hi, 0x55555555
	v_cndmask_b32_dpp v208, v210, v204, vcc quad_perm:[1,0,3,2] row_mask:0xf bank_mask:0xf
	v_cndmask_b32_dpp v209, v211, v205, vcc quad_perm:[1,0,3,2] row_mask:0xf bank_mask:0xf
	v_cndmask_b32_dpp v216, v218, v206, vcc quad_perm:[1,0,3,2] row_mask:0xf bank_mask:0xf
	v_cndmask_b32_dpp v217, v219, v207, vcc quad_perm:[1,0,3,2] row_mask:0xf bank_mask:0xf
	s_not_b64 vcc, vcc
	v_cndmask_b32_dpp v210, v204, v210, vcc quad_perm:[1,0,3,2] row_mask:0xf bank_mask:0xf
	v_cndmask_b32_dpp v211, v205, v211, vcc quad_perm:[1,0,3,2] row_mask:0xf bank_mask:0xf
	v_cndmask_b32_dpp v218, v206, v218, vcc quad_perm:[1,0,3,2] row_mask:0xf bank_mask:0xf
	v_cndmask_b32_dpp v219, v207, v219, vcc quad_perm:[1,0,3,2] row_mask:0xf bank_mask:0xf
	global_store_dwordx4 v220, v[208:211], s[6:7]
	s_add_u32 s6, s3, 0xe00
	s_addc_u32 s7, s4, 0
	s_mov_b64 s[12:13], 0
	s_add_u32 s6, s3, 0x1600
	s_addc_u32 s7, s4, 0
	global_store_dwordx4 v220, v[216:219], s[6:7]
	s_add_u32 s6, s3, 0x1e00
	s_addc_u32 s7, s4, 0

; __device__ __forceinline__ float row16_sum(float v) { v += dppf<0xB1>(v); v += dppf<0x4E>(v); v += dppf<0x141>(v); v += dppf<0x140>(v); return v; }
; __device__ __forceinline__ float frsq(float x) { return __builtin_amdgcn_rsqf(x); }
; __device__ __forceinline__ v2u pack4(const f32x4 v) { v2u r; r.x = pk2(v[0], v[1]); r.y = pk2(v[2], v[3]); return r; }
; __device__ __forceinline__ f32x4 unpack4(const v2u w) { f32x4 r; r[0] = bflo(w.x); r[1] = bfhi(w.x); r[2] = bflo(w.y); r[3] = bfhi(w.y); return r; }
; __device__ __forceinline__ const char* upin(const char* p) { asm volatile("" : "+s"(p)); return p; }
; __device__ __forceinline__ char* upin(char* p) { asm volatile("" : "+s"(p)); return p; }
; template <bool GDN> __device__ __forceinline__ void scan_finish(const Frame& F, int b, int h, int dir, const ScanLane& L, int s, float* PEND, const f32x4 (&Oin)[4], const ScanFin& f) {
;     const int cidx = dir ? (s < 4 ? 3 - s : 39 - s) : s; const int row0 = chunk_row0(b, cidx);
;     if (scan_first(s)) {
;         char* pp = upin((char*)PEND + (size_t)((b * 4 + h) * 36 + cidx) * 16384);
; #pragma unroll
;         for (int pr = 0; pr < 2; ++pr) { const v2u a = pack4(Oin[2 * pr]), bq = pack4(Oin[2 * pr + 1]); v4u o; o.x = a.x; o.y = a.y; o.z = bq.x; o.w = bq.y; stu<v4u>(pp + pr * 1024, L.pend, o); }
;     } else {
;         f32x4 O[4]; float ss[4] = {0.f, 0.f, 0.f, 0.f};
; #pragma unroll
;         for (int t = 0; t < 4; ++t)
;             { const f32x4 pv = unpack4(f.pend[t]);
; #pragma unroll
;             for (int i = 0; i < 4; ++i) { O[t][i] = Oin[t][i] + pv[i]; ss[i] += O[t][i] * O[t][i]; } }
; #pragma unroll
;         for (int i = 0; i < 4; ++i) ss[i] = frsq(row16_sum(ss[i]) * (1.f / 64.f) + EPS);
;         char* mp = (char*)F.MIX + ((size_t)row0 * 1024 + (GDN ? 0 : 768) + h * 64) * 2;
; #pragma unroll
;         for (int i = 0; i < 4; ++i) { const f32x4 g = unpack4(f.gz[i]); f32x4 ov;
; #pragma unroll
;             for (int t = 0; t < 4; ++t) ov[t] = O[t][i] * ss[i] * g[t];
;             stu<v2u>(upin(mp + i * 2048), L.mix, pack4(ov)); }
.LBB0_385:
	s_cmp_gt_u32 s25, 3
	s_cselect_b32 s5, 39, 3
	s_add_i32 s5, s5, s24
	s_add_i32 s1, s5, 3
	s_and_b64 s[6:7], s[90:91], exec
	s_cselect_b32 s1, s25, s1
	s_cmp_lt_u32 s4, 5
	s_cselect_b32 s3, 2, 20
	s_cmp_lt_u32 s25, s3
	s_mov_b64 s[12:13], -1
	s_cbranch_scc1 .LBB0_387
	s_lshl_b32 s3, s1, 6
	s_cmp_lt_i32 s1, 4
	s_cselect_b32 s6, s63, s33
	s_add_i32 s6, s6, s3
	s_ashr_i32 s7, s6, 31
	s_lshl_b64 s[6:7], s[6:7], 11
	s_add_u32 s3, s26, s6
	s_addc_u32 s6, s27, s7
	s_add_u32 s8, s3, 0x600
	s_addc_u32 s9, s6, 0
	v_lshlrev_b32_e32 v208, 16, v4
	v_and_b32_e32 v209, 0xffff0000, v4
	v_lshlrev_b32_e32 v210, 16, v5
	v_and_b32_e32 v211, 0xffff0000, v5
	v_pk_add_f32 v[212:213], v[104:105], v[208:209]
	v_pk_add_f32 v[214:215], v[106:107], v[210:211]
	v_pk_mul_f32 v[204:205], v[212:213], v[212:213]
	v_pk_mul_f32 v[206:207], v[214:215], v[214:215]
	v_lshlrev_b32_e32 v208, 16, v6
	v_and_b32_e32 v209, 0xffff0000, v6
	v_lshlrev_b32_e32 v210, 16, v7
	v_and_b32_e32 v211, 0xffff0000, v7
	v_pk_add_f32 v[216:217], v[108:109], v[208:209]
	v_pk_add_f32 v[218:219], v[110:111], v[210:211]
	v_pk_fma_f32 v[204:205], v[216:217], v[216:217], v[204:205]
	v_pk_fma_f32 v[206:207], v[218:219], v[218:219], v[206:207]
	v_lshlrev_b32_e32 v208, 16, v8
	v_and_b32_e32 v209, 0xffff0000, v8
	v_lshlrev_b32_e32 v210, 16, v9
	v_and_b32_e32 v211, 0xffff0000, v9
	v_pk_add_f32 v[224:225], v[112:113], v[208:209]
	v_pk_add_f32 v[226:227], v[114:115], v[210:211]
	v_pk_fma_f32 v[204:205], v[224:225], v[224:225], v[204:205]
	v_pk_fma_f32 v[206:207], v[226:227], v[226:227], v[206:207]
	v_lshlrev_b32_e32 v208, 16, v10
	v_and_b32_e32 v209, 0xffff0000, v10
	v_lshlrev_b32_e32 v210, 16, v11
	v_and_b32_e32 v211, 0xffff0000, v11
	v_pk_add_f32 v[242:243], v[116:117], v[208:209]
	v_pk_add_f32 v[244:245], v[118:119], v[210:211]
	v_pk_fma_f32 v[204:205], v[242:243], v[242:243], v[204:205]
	v_pk_fma_f32 v[206:207], v[244:245], v[244:245], v[206:207]
	s_nop 1
	v_add_f32_dpp v204, v204, v204 quad_perm:[1,0,3,2] row_mask:0xf bank_mask:0xf bound_ctrl:1
	v_add_f32_dpp v205, v205, v205 quad_perm:[1,0,3,2] row_mask:0xf bank_mask:0xf bound_ctrl:1
	v_add_f32_dpp v206, v206, v206 quad_perm:[1,0,3,2] row_mask:0xf bank_mask:0xf bound_ctrl:1
	v_add_f32_dpp v207, v207, v207 quad_perm:[1,0,3,2] row_mask:0xf bank_mask:0xf bound_ctrl:1
	v_add_f32_dpp v204, v204, v204 quad_perm:[2,3,0,1] row_mask:0xf bank_mask:0xf bound_ctrl:1
	v_add_f32_dpp v205, v205, v205 quad_perm:[2,3,0,1] row_mask:0xf bank_mask:0xf bound_ctrl:1
	v_add_f32_dpp v206, v206, v206 quad_perm:[2,3,0,1] row_mask:0xf bank_mask:0xf bound_ctrl:1
	v_add_f32_dpp v207, v207, v207 quad_perm:[2,3,0,1] row_mask:0xf bank_mask:0xf bound_ctrl:1
	v_add_f32_dpp v204, v204, v204 row_half_mirror row_mask:0xf bank_mask:0xf bound_ctrl:1
	v_add_f32_dpp v205, v205, v205 row_half_mirror row_mask:0xf bank_mask:0xf bound_ctrl:1
	v_add_f32_dpp v206, v206, v206 row_half_mirror row_mask:0xf bank_mask:0xf bound_ctrl:1
	v_add_f32_dpp v207, v207, v207 row_half_mirror row_mask:0xf bank_mask:0xf bound_ctrl:1
	v_add_f32_dpp v204, v204, v204 row_mirror row_mask:0xf bank_mask:0xf bound_ctrl:1
	v_add_f32_dpp v205, v205, v205 row_mirror row_mask:0xf bank_mask:0xf bound_ctrl:1
	v_add_f32_dpp v206, v206, v206 row_mirror row_mask:0xf bank_mask:0xf bound_ctrl:1
	v_add_f32_dpp v207, v207, v207 row_mirror row_mask:0xf bank_mask:0xf bound_ctrl:1
	v_fmamk_f32 v204, v204, 0x3c800000, v231
	v_fmamk_f32 v205, v205, 0x3c800000, v231
	v_fmamk_f32 v206, v206, 0x3c800000, v231
	v_fmamk_f32 v207, v207, 0x3c800000, v231
	v_rsq_f32_e32 v204, v204
	v_rsq_f32_e32 v205, v205
	v_rsq_f32_e32 v206, v206
	v_rsq_f32_e32 v207, v207
	v_lshlrev_b32_e32 v208, 16, v122
	v_lshlrev_b32_e32 v209, 16, v124
	v_lshlrev_b32_e32 v210, 16, v126
	v_lshlrev_b32_e32 v211, 16, v128
	v_pk_mul_f32 v[212:213], v[212:213], v[204:205]
	v_pk_mul_f32 v[214:215], v[214:215], v[206:207]
	v_pk_mul_f32 v[212:213], v[212:213], v[208:209]
	v_pk_mul_f32 v[214:215], v[214:215], v[210:211]
	v_and_b32_e32 v208, 0xffff0000, v122
	v_and_b32_e32 v209, 0xffff0000, v124
	v_and_b32_e32 v210, 0xffff0000, v126
	v_and_b32_e32 v211, 0xffff0000, v128
	v_pk_mul_f32 v[216:217], v[216:217], v[204:205]
	v_pk_mul_f32 v[218:219], v[218:219], v[206:207]
	v_pk_mul_f32 v[216:217], v[216:217], v[208:209]
	v_pk_mul_f32 v[218:219], v[218:219], v[210:211]
	v_lshlrev_b32_e32 v208, 16, v123
	v_lshlrev_b32_e32 v209, 16, v125
	v_lshlrev_b32_e32 v210, 16, v127
	v_lshlrev_b32_e32 v211, 16, v129
	v_pk_mul_f32 v[224:225], v[224:225], v[204:205]
	v_pk_mul_f32 v[226:227], v[226:227], v[206:207]
	v_pk_mul_f32 v[224:225], v[224:225], v[208:209]
	v_pk_mul_f32 v[226:227], v[226:227], v[210:211]
	v_and_b32_e32 v208, 0xffff0000, v123
	v_and_b32_e32 v209, 0xffff0000, v125
	v_and_b32_e32 v210, 0xffff0000, v127
	v_and_b32_e32 v211, 0xffff0000, v129
	v_pk_mul_f32 v[242:243], v[242:243], v[204:205]
	v_pk_mul_f32 v[244:245], v[244:245], v[206:207]
	v_pk_mul_f32 v[242:243], v[242:243], v[208:209]
	v_pk_mul_f32 v[244:245], v[244:245], v[210:211]
	v_cvt_pk_bf16_f32 v204, v212, v216
	v_cvt_pk_bf16_f32 v205, v224, v242
	v_cvt_pk_bf16_f32 v210, v213, v217
	v_cvt_pk_bf16_f32 v211, v225, v243
	v_cvt_pk_bf16_f32 v206, v214, v218
	v_cvt_pk_bf16_f32 v207, v226, v244
	v_cvt_pk_bf16_f32 v218, v215, v219
	v_cvt_pk_bf16_f32 v219, v227, v245
	v_and_b32_e32 v220, 1, v232
	v_mul_u32_u24_e32 v220, 0x7f8, v220
	v_add_u32_e32 v220, v39, v220
	s_mov_b32 vcc_lo, 0x55555555
	s_mov_b32 vcc_hi, 0x55555555
	v_cndmask_b32_dpp v208, v210, v204, vcc quad_perm:[1,0,3,2] row_mask:0xf bank_mask:0xf
	v_cndmask_b32_dpp v209, v211, v205, vcc quad_perm:[1,0,3,2] row_mask:0xf bank_mask:0xf
	v_cndmask_b32_dpp v216, v218, v206, vcc quad_perm:[1,0,3,2] row_mask:0xf bank_mask:0xf
	v_cndmask_b32_dpp v217, v219, v207, vcc quad_perm:[1,0,3,2] row_mask:0xf bank_mask:0xf
	s_not_b64 vcc, vcc
	v_cndmask_b32_dpp v210, v204, v210, vcc quad_perm:[1,0,3,2] row_mask:0xf bank_mask:0xf
	v_cndmask_b32_dpp v211, v205, v211, vcc quad_perm:[1,0,3,2] row_mask:0xf bank_mask:0xf
	v_cndmask_b32_dpp v218, v206, v218, vcc quad_perm:[1,0,3,2] row_mask:0xf bank_mask:0xf
	v_cndmask_b32_dpp v219, v207, v219, vcc quad_perm:[1,0,3,2] row_mask:0xf bank_mask:0xf
	global_store_dwordx4 v220, v[208:211], s[8:9]
	s_add_u32 s8, s3, 0xe00
	s_addc_u32 s9, s6, 0
	s_mov_b64 s[12:13], 0
	s_add_u32 s8, s3, 0x1600
	s_addc_u32 s9, s6, 0
	global_store_dwordx4 v220, v[216:219], s[8:9]
	s_add_u32 s8, s3, 0x1e00
	s_addc_u32 s9, s6, 0

; __device__ __forceinline__ float row16_sum(float v) { v += dppf<0xB1>(v); v += dppf<0x4E>(v); v += dppf<0x141>(v); v += dppf<0x140>(v); return v; }
; __device__ __forceinline__ float frsq(float x) { return __builtin_amdgcn_rsqf(x); }
; __device__ __forceinline__ v2u pack4(const f32x4 v) { v2u r; r.x = pk2(v[0], v[1]); r.y = pk2(v[2], v[3]); return r; }
; __device__ __forceinline__ f32x4 unpack4(const v2u w) { f32x4 r; r[0] = bflo(w.x); r[1] = bfhi(w.x); r[2] = bflo(w.y); r[3] = bfhi(w.y); return r; }
; __device__ __forceinline__ const char* upin(const char* p) { asm volatile("" : "+s"(p)); return p; }
; __device__ __forceinline__ char* upin(char* p) { asm volatile("" : "+s"(p)); return p; }
; template <bool GDN> __device__ __forceinline__ void scan_finish(const Frame& F, int b, int h, int dir, const ScanLane& L, int s, float* PEND, const f32x4 (&Oin)[4], const ScanFin& f) {
;     ...
;         f32x4 O[4]; float ss[4] = {0.f, 0.f, 0.f, 0.f};
; #pragma unroll
;         for (int t = 0; t < 4; ++t)
;             { const f32x4 pv = unpack4(f.pend[t]);
; #pragma unroll
;             for (int i = 0; i < 4; ++i) { O[t][i] = Oin[t][i] + pv[i]; ss[i] += O[t][i] * O[t][i]; } }
; #pragma unroll
;         for (int i = 0; i < 4; ++i) ss[i] = frsq(row16_sum(ss[i]) * (1.f / 64.f) + EPS);
;         char* mp = (char*)F.MIX + ((size_t)row0 * 1024 + (GDN ? 0 : 768) + h * 64) * 2;
; #pragma unroll
;         for (int i = 0; i < 4; ++i) { const f32x4 g = unpack4(f.gz[i]); f32x4 ov;
; #pragma unroll
;             for (int t = 0; t < 4; ++t) ov[t] = O[t][i] * ss[i] * g[t];
;             stu<v2u>(upin(mp + i * 2048), L.mix, pack4(ov)); }
.LBB0_434:
	s_lshl_b32 s3, s4, 6
	s_cmp_lt_i32 s4, 4
	s_cselect_b32 s5, s63, s33
	s_add_i32 s6, s5, s3
	s_ashr_i32 s7, s6, 31
	s_lshl_b64 s[6:7], s[6:7], 11
	s_add_u32 s3, s26, s6
	s_addc_u32 s5, s27, s7
	s_add_u32 s6, s3, 0x600
	s_addc_u32 s7, s5, 0
	v_lshlrev_b32_e32 v208, 16, v4
	v_and_b32_e32 v209, 0xffff0000, v4
	v_lshlrev_b32_e32 v210, 16, v5
	v_and_b32_e32 v211, 0xffff0000, v5
	v_pk_add_f32 v[212:213], v[50:51], v[208:209]
	v_pk_add_f32 v[214:215], v[2:3], v[210:211]
	v_pk_mul_f32 v[204:205], v[212:213], v[212:213]
	v_pk_mul_f32 v[206:207], v[214:215], v[214:215]
	v_lshlrev_b32_e32 v208, 16, v6
	v_and_b32_e32 v209, 0xffff0000, v6
	v_lshlrev_b32_e32 v210, 16, v7
	v_and_b32_e32 v211, 0xffff0000, v7
	v_pk_add_f32 v[216:217], v[112:113], v[208:209]
	v_pk_add_f32 v[218:219], v[118:119], v[210:211]
	v_pk_fma_f32 v[204:205], v[216:217], v[216:217], v[204:205]
	v_pk_fma_f32 v[206:207], v[218:219], v[218:219], v[206:207]
	v_lshlrev_b32_e32 v208, 16, v8
	v_and_b32_e32 v209, 0xffff0000, v8
	v_lshlrev_b32_e32 v210, 16, v9
	v_and_b32_e32 v211, 0xffff0000, v9
	v_pk_add_f32 v[224:225], v[56:57], v[208:209]
	v_pk_add_f32 v[226:227], v[48:49], v[210:211]
	v_pk_fma_f32 v[204:205], v[224:225], v[224:225], v[204:205]
	v_pk_fma_f32 v[206:207], v[226:227], v[226:227], v[206:207]
	v_lshlrev_b32_e32 v208, 16, v10
	v_and_b32_e32 v209, 0xffff0000, v10
	v_lshlrev_b32_e32 v210, 16, v11
	v_and_b32_e32 v211, 0xffff0000, v11
	v_pk_add_f32 v[242:243], v[114:115], v[208:209]
	v_pk_add_f32 v[244:245], v[116:117], v[210:211]
	v_pk_fma_f32 v[204:205], v[242:243], v[242:243], v[204:205]
	v_pk_fma_f32 v[206:207], v[244:245], v[244:245], v[206:207]
	s_nop 1
	v_add_f32_dpp v204, v204, v204 quad_perm:[1,0,3,2] row_mask:0xf bank_mask:0xf bound_ctrl:1
	v_add_f32_dpp v205, v205, v205 quad_perm:[1,0,3,2] row_mask:0xf bank_mask:0xf bound_ctrl:1
	v_add_f32_dpp v206, v206, v206 quad_perm:[1,0,3,2] row_mask:0xf bank_mask:0xf bound_ctrl:1
	v_add_f32_dpp v207, v207, v207 quad_perm:[1,0,3,2] row_mask:0xf bank_mask:0xf bound_ctrl:1
	v_add_f32_dpp v204, v204, v204 quad_perm:[2,3,0,1] row_mask:0xf bank_mask:0xf bound_ctrl:1
	v_add_f32_dpp v205, v205, v205 quad_perm:[2,3,0,1] row_mask:0xf bank_mask:0xf bound_ctrl:1
	v_add_f32_dpp v206, v206, v206 quad_perm:[2,3,0,1] row_mask:0xf bank_mask:0xf bound_ctrl:1
	v_add_f32_dpp v207, v207, v207 quad_perm:[2,3,0,1] row_mask:0xf bank_mask:0xf bound_ctrl:1
	v_add_f32_dpp v204, v204, v204 row_half_mirror row_mask:0xf bank_mask:0xf bound_ctrl:1
	v_add_f32_dpp v205, v205, v205 row_half_mirror row_mask:0xf bank_mask:0xf bound_ctrl:1
	v_add_f32_dpp v206, v206, v206 row_half_mirror row_mask:0xf bank_mask:0xf bound_ctrl:1
	v_add_f32_dpp v207, v207, v207 row_half_mirror row_mask:0xf bank_mask:0xf bound_ctrl:1
	v_add_f32_dpp v204, v204, v204 row_mirror row_mask:0xf bank_mask:0xf bound_ctrl:1
	v_add_f32_dpp v205, v205, v205 row_mirror row_mask:0xf bank_mask:0xf bound_ctrl:1
	v_add_f32_dpp v206, v206, v206 row_mirror row_mask:0xf bank_mask:0xf bound_ctrl:1
	v_add_f32_dpp v207, v207, v207 row_mirror row_mask:0xf bank_mask:0xf bound_ctrl:1
	v_fmamk_f32 v204, v204, 0x3c800000, v231
	v_fmamk_f32 v205, v205, 0x3c800000, v231
	v_fmamk_f32 v206, v206, 0x3c800000, v231
	v_fmamk_f32 v207, v207, 0x3c800000, v231
	v_rsq_f32_e32 v204, v204
	v_rsq_f32_e32 v205, v205
	v_rsq_f32_e32 v206, v206
	v_rsq_f32_e32 v207, v207
	v_lshlrev_b32_e32 v208, 16, v122
	v_lshlrev_b32_e32 v209, 16, v124
	v_lshlrev_b32_e32 v210, 16, v126
	v_lshlrev_b32_e32 v211, 16, v128
	v_pk_mul_f32 v[212:213], v[212:213], v[204:205]
	v_pk_mul_f32 v[214:215], v[214:215], v[206:207]
	v_pk_mul_f32 v[212:213], v[212:213], v[208:209]
	v_pk_mul_f32 v[214:215], v[214:215], v[210:211]
	v_and_b32_e32 v208, 0xffff0000, v122
	v_and_b32_e32 v209, 0xffff0000, v124
	v_and_b32_e32 v210, 0xffff0000, v126
	v_and_b32_e32 v211, 0xffff0000, v128
	v_pk_mul_f32 v[216:217], v[216:217], v[204:205]
	v_pk_mul_f32 v[218:219], v[218:219], v[206:207]
	v_pk_mul_f32 v[216:217], v[216:217], v[208:209]
	v_pk_mul_f32 v[218:219], v[218:219], v[210:211]
	v_lshlrev_b32_e32 v208, 16, v123
	v_lshlrev_b32_e32 v209, 16, v125
	v_lshlrev_b32_e32 v210, 16, v127
	v_lshlrev_b32_e32 v211, 16, v129
	v_pk_mul_f32 v[224:225], v[224:225], v[204:205]
	v_pk_mul_f32 v[226:227], v[226:227], v[206:207]
	v_pk_mul_f32 v[224:225], v[224:225], v[208:209]
	v_pk_mul_f32 v[226:227], v[226:227], v[210:211]
	v_and_b32_e32 v208, 0xffff0000, v123
	v_and_b32_e32 v209, 0xffff0000, v125
	v_and_b32_e32 v210, 0xffff0000, v127
	v_and_b32_e32 v211, 0xffff0000, v129
	v_pk_mul_f32 v[242:243], v[242:243], v[204:205]
	v_pk_mul_f32 v[244:245], v[244:245], v[206:207]
	v_pk_mul_f32 v[242:243], v[242:243], v[208:209]
	v_pk_mul_f32 v[244:245], v[244:245], v[210:211]
	v_cvt_pk_bf16_f32 v204, v212, v216
	v_cvt_pk_bf16_f32 v205, v224, v242
	v_cvt_pk_bf16_f32 v210, v213, v217
	v_cvt_pk_bf16_f32 v211, v225, v243
	v_cvt_pk_bf16_f32 v206, v214, v218
	v_cvt_pk_bf16_f32 v207, v226, v244
	v_cvt_pk_bf16_f32 v218, v215, v219
	v_cvt_pk_bf16_f32 v219, v227, v245
	v_and_b32_e32 v220, 1, v232
	v_mul_u32_u24_e32 v220, 0x7f8, v220
	v_add_u32_e32 v220, v75, v220
	s_mov_b32 vcc_lo, 0x55555555
	s_mov_b32 vcc_hi, 0x55555555
	v_cndmask_b32_dpp v208, v210, v204, vcc quad_perm:[1,0,3,2] row_mask:0xf bank_mask:0xf
	v_cndmask_b32_dpp v209, v211, v205, vcc quad_perm:[1,0,3,2] row_mask:0xf bank_mask:0xf
	v_cndmask_b32_dpp v216, v218, v206, vcc quad_perm:[1,0,3,2] row_mask:0xf bank_mask:0xf
	v_cndmask_b32_dpp v217, v219, v207, vcc quad_perm:[1,0,3,2] row_mask:0xf bank_mask:0xf
	s_not_b64 vcc, vcc
	v_cndmask_b32_dpp v210, v204, v210, vcc quad_perm:[1,0,3,2] row_mask:0xf bank_mask:0xf
	v_cndmask_b32_dpp v211, v205, v211, vcc quad_perm:[1,0,3,2] row_mask:0xf bank_mask:0xf
	v_cndmask_b32_dpp v218, v206, v218, vcc quad_perm:[1,0,3,2] row_mask:0xf bank_mask:0xf
	v_cndmask_b32_dpp v219, v207, v219, vcc quad_perm:[1,0,3,2] row_mask:0xf bank_mask:0xf
	global_store_dwordx4 v220, v[208:211], s[6:7]
	s_add_u32 s6, s3, 0xe00
	s_addc_u32 s7, s5, 0
	s_add_u32 s6, s3, 0x1600
	s_addc_u32 s7, s5, 0
	global_store_dwordx4 v220, v[216:219], s[6:7]
	s_add_u32 s6, s3, 0x1e00
	s_addc_u32 s7, s5, 0
	s_cbranch_execz .LBB0_450

; __device__ __forceinline__ float row16_sum(float v) { v += dppf<0xB1>(v); v += dppf<0x4E>(v); v += dppf<0x141>(v); v += dppf<0x140>(v); return v; }
; __device__ __forceinline__ float frsq(float x) { return __builtin_amdgcn_rsqf(x); }
; __device__ __forceinline__ v2u pack4(const f32x4 v) { v2u r; r.x = pk2(v[0], v[1]); r.y = pk2(v[2], v[3]); return r; }
; __device__ __forceinline__ f32x4 unpack4(const v2u w) { f32x4 r; r[0] = bflo(w.x); r[1] = bfhi(w.x); r[2] = bflo(w.y); r[3] = bfhi(w.y); return r; }
; __device__ __forceinline__ const char* upin(const char* p) { asm volatile("" : "+s"(p)); return p; }
; __device__ __forceinline__ char* upin(char* p) { asm volatile("" : "+s"(p)); return p; }
; template <bool GDN> __device__ __forceinline__ void scan_finish(const Frame& F, int b, int h, int dir, const ScanLane& L, int s, float* PEND, const f32x4 (&Oin)[4], const ScanFin& f) {
;     ...
;         f32x4 O[4]; float ss[4] = {0.f, 0.f, 0.f, 0.f};
; #pragma unroll
;         for (int t = 0; t < 4; ++t)
;             { const f32x4 pv = unpack4(f.pend[t]);
; #pragma unroll
;             for (int i = 0; i < 4; ++i) { O[t][i] = Oin[t][i] + pv[i]; ss[i] += O[t][i] * O[t][i]; } }
; #pragma unroll
;         for (int i = 0; i < 4; ++i) ss[i] = frsq(row16_sum(ss[i]) * (1.f / 64.f) + EPS);
;         char* mp = (char*)F.MIX + ((size_t)row0 * 1024 + (GDN ? 0 : 768) + h * 64) * 2;
; #pragma unroll
;         for (int i = 0; i < 4; ++i) { const f32x4 g = unpack4(f.gz[i]); f32x4 ov;
; #pragma unroll
;             for (int t = 0; t < 4; ++t) ov[t] = O[t][i] * ss[i] * g[t];
;             stu<v2u>(upin(mp + i * 2048), L.mix, pack4(ov)); }
.LBB0_469:
	s_lshl_b32 s1, s0, 6
	s_cmp_lt_i32 s0, 4
	s_cselect_b32 s3, s63, s33
	s_add_i32 s4, s3, s1
	s_ashr_i32 s5, s4, 31
	s_lshl_b64 s[4:5], s[4:5], 11
	s_add_u32 s1, s26, s4
	s_addc_u32 s3, s27, s5
	s_add_u32 s4, s1, 0x600
	s_addc_u32 s5, s3, 0
	v_lshlrev_b32_e32 v208, 16, v4
	v_and_b32_e32 v209, 0xffff0000, v4
	v_lshlrev_b32_e32 v210, 16, v5
	v_and_b32_e32 v211, 0xffff0000, v5
	v_pk_add_f32 v[212:213], v[24:25], v[208:209]
	v_pk_add_f32 v[214:215], v[20:21], v[210:211]
	v_pk_mul_f32 v[204:205], v[212:213], v[212:213]
	v_pk_mul_f32 v[206:207], v[214:215], v[214:215]
	v_lshlrev_b32_e32 v208, 16, v6
	v_and_b32_e32 v209, 0xffff0000, v6
	v_lshlrev_b32_e32 v210, 16, v7
	v_and_b32_e32 v211, 0xffff0000, v7
	v_pk_add_f32 v[216:217], v[104:105], v[208:209]
	v_pk_add_f32 v[218:219], v[110:111], v[210:211]
	v_pk_fma_f32 v[204:205], v[216:217], v[216:217], v[204:205]
	v_pk_fma_f32 v[206:207], v[218:219], v[218:219], v[206:207]
	v_lshlrev_b32_e32 v208, 16, v8
	v_and_b32_e32 v209, 0xffff0000, v8
	v_lshlrev_b32_e32 v210, 16, v9
	v_and_b32_e32 v211, 0xffff0000, v9
	v_pk_add_f32 v[224:225], v[26:27], v[208:209]
	v_pk_add_f32 v[226:227], v[22:23], v[210:211]
	v_pk_fma_f32 v[204:205], v[224:225], v[224:225], v[204:205]
	v_pk_fma_f32 v[206:207], v[226:227], v[226:227], v[206:207]
	v_lshlrev_b32_e32 v208, 16, v10
	v_and_b32_e32 v209, 0xffff0000, v10
	v_lshlrev_b32_e32 v210, 16, v11
	v_and_b32_e32 v211, 0xffff0000, v11
	v_pk_add_f32 v[242:243], v[106:107], v[208:209]
	v_pk_add_f32 v[244:245], v[108:109], v[210:211]
	v_pk_fma_f32 v[204:205], v[242:243], v[242:243], v[204:205]
	v_pk_fma_f32 v[206:207], v[244:245], v[244:245], v[206:207]
	s_nop 1
	v_add_f32_dpp v204, v204, v204 quad_perm:[1,0,3,2] row_mask:0xf bank_mask:0xf bound_ctrl:1
	v_add_f32_dpp v205, v205, v205 quad_perm:[1,0,3,2] row_mask:0xf bank_mask:0xf bound_ctrl:1
	v_add_f32_dpp v206, v206, v206 quad_perm:[1,0,3,2] row_mask:0xf bank_mask:0xf bound_ctrl:1
	v_add_f32_dpp v207, v207, v207 quad_perm:[1,0,3,2] row_mask:0xf bank_mask:0xf bound_ctrl:1
	v_add_f32_dpp v204, v204, v204 quad_perm:[2,3,0,1] row_mask:0xf bank_mask:0xf bound_ctrl:1
	v_add_f32_dpp v205, v205, v205 quad_perm:[2,3,0,1] row_mask:0xf bank_mask:0xf bound_ctrl:1
	v_add_f32_dpp v206, v206, v206 quad_perm:[2,3,0,1] row_mask:0xf bank_mask:0xf bound_ctrl:1
	v_add_f32_dpp v207, v207, v207 quad_perm:[2,3,0,1] row_mask:0xf bank_mask:0xf bound_ctrl:1
	v_add_f32_dpp v204, v204, v204 row_half_mirror row_mask:0xf bank_mask:0xf bound_ctrl:1
	v_add_f32_dpp v205, v205, v205 row_half_mirror row_mask:0xf bank_mask:0xf bound_ctrl:1
	v_add_f32_dpp v206, v206, v206 row_half_mirror row_mask:0xf bank_mask:0xf bound_ctrl:1
	v_add_f32_dpp v207, v207, v207 row_half_mirror row_mask:0xf bank_mask:0xf bound_ctrl:1
	v_add_f32_dpp v204, v204, v204 row_mirror row_mask:0xf bank_mask:0xf bound_ctrl:1
	v_add_f32_dpp v205, v205, v205 row_mirror row_mask:0xf bank_mask:0xf bound_ctrl:1
	v_add_f32_dpp v206, v206, v206 row_mirror row_mask:0xf bank_mask:0xf bound_ctrl:1
	v_add_f32_dpp v207, v207, v207 row_mirror row_mask:0xf bank_mask:0xf bound_ctrl:1
	v_fmamk_f32 v204, v204, 0x3c800000, v231
	v_fmamk_f32 v205, v205, 0x3c800000, v231
	v_fmamk_f32 v206, v206, 0x3c800000, v231
	v_fmamk_f32 v207, v207, 0x3c800000, v231
	v_rsq_f32_e32 v204, v204
	v_rsq_f32_e32 v205, v205
	v_rsq_f32_e32 v206, v206
	v_rsq_f32_e32 v207, v207
	v_lshlrev_b32_e32 v208, 16, v122
	v_lshlrev_b32_e32 v209, 16, v124
	v_lshlrev_b32_e32 v210, 16, v126
	v_lshlrev_b32_e32 v211, 16, v128
	v_pk_mul_f32 v[212:213], v[212:213], v[204:205]
	v_pk_mul_f32 v[214:215], v[214:215], v[206:207]
	v_pk_mul_f32 v[212:213], v[212:213], v[208:209]
	v_pk_mul_f32 v[214:215], v[214:215], v[210:211]
	v_and_b32_e32 v208, 0xffff0000, v122
	v_and_b32_e32 v209, 0xffff0000, v124
	v_and_b32_e32 v210, 0xffff0000, v126
	v_and_b32_e32 v211, 0xffff0000, v128
	v_pk_mul_f32 v[216:217], v[216:217], v[204:205]
	v_pk_mul_f32 v[218:219], v[218:219], v[206:207]
	v_pk_mul_f32 v[216:217], v[216:217], v[208:209]
	v_pk_mul_f32 v[218:219], v[218:219], v[210:211]
	v_lshlrev_b32_e32 v208, 16, v123
	v_lshlrev_b32_e32 v209, 16, v125
	v_lshlrev_b32_e32 v210, 16, v127
	v_lshlrev_b32_e32 v211, 16, v129
	v_pk_mul_f32 v[224:225], v[224:225], v[204:205]
	v_pk_mul_f32 v[226:227], v[226:227], v[206:207]
	v_pk_mul_f32 v[224:225], v[224:225], v[208:209]
	v_pk_mul_f32 v[226:227], v[226:227], v[210:211]
	v_and_b32_e32 v208, 0xffff0000, v123
	v_and_b32_e32 v209, 0xffff0000, v125
	v_and_b32_e32 v210, 0xffff0000, v127
	v_and_b32_e32 v211, 0xffff0000, v129
	v_pk_mul_f32 v[242:243], v[242:243], v[204:205]
	v_pk_mul_f32 v[244:245], v[244:245], v[206:207]
	v_pk_mul_f32 v[242:243], v[242:243], v[208:209]
	v_pk_mul_f32 v[244:245], v[244:245], v[210:211]
	v_cvt_pk_bf16_f32 v204, v212, v216
	v_cvt_pk_bf16_f32 v205, v224, v242
	v_cvt_pk_bf16_f32 v210, v213, v217
	v_cvt_pk_bf16_f32 v211, v225, v243
	v_cvt_pk_bf16_f32 v206, v214, v218
	v_cvt_pk_bf16_f32 v207, v226, v244
	v_cvt_pk_bf16_f32 v218, v215, v219
	v_cvt_pk_bf16_f32 v219, v227, v245
	v_and_b32_e32 v220, 1, v232
	v_mul_u32_u24_e32 v220, 0x7f8, v220
	v_add_u32_e32 v220, v31, v220
	s_mov_b32 vcc_lo, 0x55555555
	s_mov_b32 vcc_hi, 0x55555555
	v_cndmask_b32_dpp v208, v210, v204, vcc quad_perm:[1,0,3,2] row_mask:0xf bank_mask:0xf
	v_cndmask_b32_dpp v209, v211, v205, vcc quad_perm:[1,0,3,2] row_mask:0xf bank_mask:0xf
	v_cndmask_b32_dpp v216, v218, v206, vcc quad_perm:[1,0,3,2] row_mask:0xf bank_mask:0xf
	v_cndmask_b32_dpp v217, v219, v207, vcc quad_perm:[1,0,3,2] row_mask:0xf bank_mask:0xf
	s_not_b64 vcc, vcc
	v_cndmask_b32_dpp v210, v204, v210, vcc quad_perm:[1,0,3,2] row_mask:0xf bank_mask:0xf
	v_cndmask_b32_dpp v211, v205, v211, vcc quad_perm:[1,0,3,2] row_mask:0xf bank_mask:0xf
	v_cndmask_b32_dpp v218, v206, v218, vcc quad_perm:[1,0,3,2] row_mask:0xf bank_mask:0xf
	v_cndmask_b32_dpp v219, v207, v219, vcc quad_perm:[1,0,3,2] row_mask:0xf bank_mask:0xf
	global_store_dwordx4 v220, v[208:211], s[4:5]
	s_add_u32 s4, s1, 0xe00
	s_addc_u32 s5, s3, 0
	s_add_u32 s4, s1, 0x1600
	s_addc_u32 s5, s3, 0
	global_store_dwordx4 v220, v[216:219], s[4:5]
	s_add_u32 s4, s1, 0x1e00
	s_addc_u32 s5, s3, 0
	s_cbranch_execz .LBB0_474

; __device__ __forceinline__ float row16_sum(float v) { v += dppf<0xB1>(v); v += dppf<0x4E>(v); v += dppf<0x141>(v); v += dppf<0x140>(v); return v; }
; __device__ __forceinline__ float frsq(float x) { return __builtin_amdgcn_rsqf(x); }
; __device__ __forceinline__ v2u pack4(const f32x4 v) { v2u r; r.x = pk2(v[0], v[1]); r.y = pk2(v[2], v[3]); return r; }
; __device__ __forceinline__ f32x4 unpack4(const v2u w) { f32x4 r; r[0] = bflo(w.x); r[1] = bfhi(w.x); r[2] = bflo(w.y); r[3] = bfhi(w.y); return r; }
; __device__ __forceinline__ const char* upin(const char* p) { asm volatile("" : "+s"(p)); return p; }
; __device__ __forceinline__ char* upin(char* p) { asm volatile("" : "+s"(p)); return p; }
; template <bool GDN> __device__ __forceinline__ void scan_finish(const Frame& F, int b, int h, int dir, const ScanLane& L, int s, float* PEND, const f32x4 (&Oin)[4], const ScanFin& f) {
;     const int cidx = dir ? (s < 4 ? 3 - s : 39 - s) : s; const int row0 = chunk_row0(b, cidx);
;     if (scan_first(s)) {
;         char* pp = upin((char*)PEND + (size_t)((b * 4 + h) * 36 + cidx) * 16384);
; #pragma unroll
;         for (int pr = 0; pr < 2; ++pr) { const v2u a = pack4(Oin[2 * pr]), bq = pack4(Oin[2 * pr + 1]); v4u o; o.x = a.x; o.y = a.y; o.z = bq.x; o.w = bq.y; stu<v4u>(pp + pr * 1024, L.pend, o); }
;     } else {
;         f32x4 O[4]; float ss[4] = {0.f, 0.f, 0.f, 0.f};
; #pragma unroll
;         for (int t = 0; t < 4; ++t)
;             { const f32x4 pv = unpack4(f.pend[t]);
; #pragma unroll
;             for (int i = 0; i < 4; ++i) { O[t][i] = Oin[t][i] + pv[i]; ss[i] += O[t][i] * O[t][i]; } }
; #pragma unroll
;         for (int i = 0; i < 4; ++i) ss[i] = frsq(row16_sum(ss[i]) * (1.f / 64.f) + EPS);
;         char* mp = (char*)F.MIX + ((size_t)row0 * 1024 + (GDN ? 0 : 768) + h * 64) * 2;
; #pragma unroll
;         for (int i = 0; i < 4; ++i) { const f32x4 g = unpack4(f.gz[i]); f32x4 ov;
; #pragma unroll
;             for (int t = 0; t < 4; ++t) ov[t] = O[t][i] * ss[i] * g[t];
;             stu<v2u>(upin(mp + i * 2048), L.mix, pack4(ov)); }
.LBB0_487:
	s_add_i32 s0, s23, -1
	s_cmp_eq_u32 s23, 0
	s_cselect_b64 s[10:11], -1, 0
	s_and_b64 vcc, exec, s[10:11]
	s_waitcnt lgkmcnt(0)
	s_barrier
	s_cbranch_vccnz .LBB0_492
	s_add_i32 s1, s22, 43
	s_and_b64 s[4:5], s[90:91], exec
	s_cselect_b32 s1, s0, s1
	s_cmp_lt_u32 s23, 5
	s_cselect_b32 s3, 2, 20
	s_cmp_lt_u32 s0, s3
	s_mov_b64 s[12:13], -1
	s_cbranch_scc1 .LBB0_490
	s_cmp_lt_i32 s1, 4
	s_cselect_b32 s3, s25, s24
	s_lshl_b32 s4, s1, 6
	s_add_i32 s4, s3, s4
	s_ashr_i32 s5, s4, 31
	s_lshl_b64 s[4:5], s[4:5], 11
	s_add_u32 s18, s26, s4
	s_addc_u32 s19, s27, s5
	s_mov_b64 s[4:5], s[18:19]
	v_lshlrev_b32_e32 v208, 16, v10
	v_and_b32_e32 v209, 0xffff0000, v10
	v_lshlrev_b32_e32 v210, 16, v11
	v_and_b32_e32 v211, 0xffff0000, v11
	v_pk_add_f32 v[212:213], v[130:131], v[208:209]
	v_pk_add_f32 v[214:215], v[132:133], v[210:211]
	v_pk_mul_f32 v[204:205], v[212:213], v[212:213]
	v_pk_mul_f32 v[206:207], v[214:215], v[214:215]
	v_lshlrev_b32_e32 v208, 16, v12
	v_and_b32_e32 v209, 0xffff0000, v12
	v_lshlrev_b32_e32 v210, 16, v13
	v_and_b32_e32 v211, 0xffff0000, v13
	v_pk_add_f32 v[216:217], v[134:135], v[208:209]
	v_pk_add_f32 v[218:219], v[136:137], v[210:211]
	v_pk_fma_f32 v[204:205], v[216:217], v[216:217], v[204:205]
	v_pk_fma_f32 v[206:207], v[218:219], v[218:219], v[206:207]
	v_lshlrev_b32_e32 v208, 16, v14
	v_and_b32_e32 v209, 0xffff0000, v14
	v_lshlrev_b32_e32 v210, 16, v15
	v_and_b32_e32 v211, 0xffff0000, v15
	v_pk_add_f32 v[224:225], v[138:139], v[208:209]
	v_pk_add_f32 v[226:227], v[140:141], v[210:211]
	v_pk_fma_f32 v[204:205], v[224:225], v[224:225], v[204:205]
	v_pk_fma_f32 v[206:207], v[226:227], v[226:227], v[206:207]
	v_lshlrev_b32_e32 v208, 16, v16
	v_and_b32_e32 v209, 0xffff0000, v16
	v_lshlrev_b32_e32 v210, 16, v17
	v_and_b32_e32 v211, 0xffff0000, v17
	v_pk_add_f32 v[242:243], v[142:143], v[208:209]
	v_pk_add_f32 v[244:245], v[144:145], v[210:211]
	v_pk_fma_f32 v[204:205], v[242:243], v[242:243], v[204:205]
	v_pk_fma_f32 v[206:207], v[244:245], v[244:245], v[206:207]
	s_nop 1
	v_add_f32_dpp v204, v204, v204 quad_perm:[1,0,3,2] row_mask:0xf bank_mask:0xf bound_ctrl:1
	v_add_f32_dpp v205, v205, v205 quad_perm:[1,0,3,2] row_mask:0xf bank_mask:0xf bound_ctrl:1
	v_add_f32_dpp v206, v206, v206 quad_perm:[1,0,3,2] row_mask:0xf bank_mask:0xf bound_ctrl:1
	v_add_f32_dpp v207, v207, v207 quad_perm:[1,0,3,2] row_mask:0xf bank_mask:0xf bound_ctrl:1
	v_add_f32_dpp v204, v204, v204 quad_perm:[2,3,0,1] row_mask:0xf bank_mask:0xf bound_ctrl:1
	v_add_f32_dpp v205, v205, v205 quad_perm:[2,3,0,1] row_mask:0xf bank_mask:0xf bound_ctrl:1
	v_add_f32_dpp v206, v206, v206 quad_perm:[2,3,0,1] row_mask:0xf bank_mask:0xf bound_ctrl:1
	v_add_f32_dpp v207, v207, v207 quad_perm:[2,3,0,1] row_mask:0xf bank_mask:0xf bound_ctrl:1
	v_add_f32_dpp v204, v204, v204 row_half_mirror row_mask:0xf bank_mask:0xf bound_ctrl:1
	v_add_f32_dpp v205, v205, v205 row_half_mirror row_mask:0xf bank_mask:0xf bound_ctrl:1
	v_add_f32_dpp v206, v206, v206 row_half_mirror row_mask:0xf bank_mask:0xf bound_ctrl:1
	v_add_f32_dpp v207, v207, v207 row_half_mirror row_mask:0xf bank_mask:0xf bound_ctrl:1
	v_add_f32_dpp v204, v204, v204 row_mirror row_mask:0xf bank_mask:0xf bound_ctrl:1
	v_add_f32_dpp v205, v205, v205 row_mirror row_mask:0xf bank_mask:0xf bound_ctrl:1
	v_add_f32_dpp v206, v206, v206 row_mirror row_mask:0xf bank_mask:0xf bound_ctrl:1
	v_add_f32_dpp v207, v207, v207 row_mirror row_mask:0xf bank_mask:0xf bound_ctrl:1
	v_fmamk_f32 v204, v204, 0x3c800000, v231
	v_fmamk_f32 v205, v205, 0x3c800000, v231
	v_fmamk_f32 v206, v206, 0x3c800000, v231
	v_fmamk_f32 v207, v207, 0x3c800000, v231
	v_rsq_f32_e32 v204, v204
	v_rsq_f32_e32 v205, v205
	v_rsq_f32_e32 v206, v206
	v_rsq_f32_e32 v207, v207
	v_lshlrev_b32_e32 v208, 16, v164
	v_lshlrev_b32_e32 v209, 16, v178
	v_lshlrev_b32_e32 v210, 16, v180
	v_lshlrev_b32_e32 v211, 16, v182
	v_pk_mul_f32 v[212:213], v[212:213], v[204:205]
	v_pk_mul_f32 v[214:215], v[214:215], v[206:207]
	v_pk_mul_f32 v[212:213], v[212:213], v[208:209]
	v_pk_mul_f32 v[214:215], v[214:215], v[210:211]
	v_and_b32_e32 v208, 0xffff0000, v164
	v_and_b32_e32 v209, 0xffff0000, v178
	v_and_b32_e32 v210, 0xffff0000, v180
	v_and_b32_e32 v211, 0xffff0000, v182
	v_pk_mul_f32 v[216:217], v[216:217], v[204:205]
	v_pk_mul_f32 v[218:219], v[218:219], v[206:207]
	v_pk_mul_f32 v[216:217], v[216:217], v[208:209]
	v_pk_mul_f32 v[218:219], v[218:219], v[210:211]
	v_lshlrev_b32_e32 v208, 16, v165
	v_lshlrev_b32_e32 v209, 16, v179
	v_lshlrev_b32_e32 v210, 16, v181
	v_lshlrev_b32_e32 v211, 16, v183
	v_pk_mul_f32 v[224:225], v[224:225], v[204:205]
	v_pk_mul_f32 v[226:227], v[226:227], v[206:207]
	v_pk_mul_f32 v[224:225], v[224:225], v[208:209]
	v_pk_mul_f32 v[226:227], v[226:227], v[210:211]
	v_and_b32_e32 v208, 0xffff0000, v165
	v_and_b32_e32 v209, 0xffff0000, v179
	v_and_b32_e32 v210, 0xffff0000, v181
	v_and_b32_e32 v211, 0xffff0000, v183
	v_pk_mul_f32 v[242:243], v[242:243], v[204:205]
	v_pk_mul_f32 v[244:245], v[244:245], v[206:207]
	v_pk_mul_f32 v[242:243], v[242:243], v[208:209]
	v_pk_mul_f32 v[244:245], v[244:245], v[210:211]
	v_cvt_pk_bf16_f32 v204, v212, v216
	v_cvt_pk_bf16_f32 v205, v224, v242
	v_cvt_pk_bf16_f32 v210, v213, v217
	v_cvt_pk_bf16_f32 v211, v225, v243
	v_cvt_pk_bf16_f32 v206, v214, v218
	v_cvt_pk_bf16_f32 v207, v226, v244
	v_cvt_pk_bf16_f32 v218, v215, v219
	v_cvt_pk_bf16_f32 v219, v227, v245
	v_and_b32_e32 v220, 1, v232
	v_mul_u32_u24_e32 v220, 0x7f8, v220
	v_add_u32_e32 v220, v149, v220
	s_mov_b32 vcc_lo, 0x55555555
	s_mov_b32 vcc_hi, 0x55555555
	v_cndmask_b32_dpp v208, v210, v204, vcc quad_perm:[1,0,3,2] row_mask:0xf bank_mask:0xf
	v_cndmask_b32_dpp v209, v211, v205, vcc quad_perm:[1,0,3,2] row_mask:0xf bank_mask:0xf
	v_cndmask_b32_dpp v216, v218, v206, vcc quad_perm:[1,0,3,2] row_mask:0xf bank_mask:0xf
	v_cndmask_b32_dpp v217, v219, v207, vcc quad_perm:[1,0,3,2] row_mask:0xf bank_mask:0xf
	s_not_b64 vcc, vcc
	v_cndmask_b32_dpp v210, v204, v210, vcc quad_perm:[1,0,3,2] row_mask:0xf bank_mask:0xf
	v_cndmask_b32_dpp v211, v205, v211, vcc quad_perm:[1,0,3,2] row_mask:0xf bank_mask:0xf
	v_cndmask_b32_dpp v218, v206, v218, vcc quad_perm:[1,0,3,2] row_mask:0xf bank_mask:0xf
	v_cndmask_b32_dpp v219, v207, v219, vcc quad_perm:[1,0,3,2] row_mask:0xf bank_mask:0xf
	global_store_dwordx4 v220, v[208:211], s[4:5]
	s_add_u32 s4, s18, 0x800
	s_addc_u32 s5, s19, 0
	s_mov_b64 s[12:13], 0
	s_add_u32 s4, s18, 0x1000
	s_addc_u32 s5, s19, 0
	global_store_dwordx4 v220, v[216:219], s[4:5]
	s_add_u32 s4, s18, 0x1800
	s_addc_u32 s5, s19, 0

; __device__ __forceinline__ float row16_sum(float v) { v += dppf<0xB1>(v); v += dppf<0x4E>(v); v += dppf<0x141>(v); v += dppf<0x140>(v); return v; }
; __device__ __forceinline__ float frsq(float x) { return __builtin_amdgcn_rsqf(x); }
; __device__ __forceinline__ v2u pack4(const f32x4 v) { v2u r; r.x = pk2(v[0], v[1]); r.y = pk2(v[2], v[3]); return r; }
; __device__ __forceinline__ f32x4 unpack4(const v2u w) { f32x4 r; r[0] = bflo(w.x); r[1] = bfhi(w.x); r[2] = bflo(w.y); r[3] = bfhi(w.y); return r; }
; __device__ __forceinline__ const char* upin(const char* p) { asm volatile("" : "+s"(p)); return p; }
; __device__ __forceinline__ char* upin(char* p) { asm volatile("" : "+s"(p)); return p; }
; template <bool GDN> __device__ __forceinline__ void scan_finish(const Frame& F, int b, int h, int dir, const ScanLane& L, int s, float* PEND, const f32x4 (&Oin)[4], const ScanFin& f) {
;     const int cidx = dir ? (s < 4 ? 3 - s : 39 - s) : s; const int row0 = chunk_row0(b, cidx);
;     if (scan_first(s)) {
;         char* pp = upin((char*)PEND + (size_t)((b * 4 + h) * 36 + cidx) * 16384);
; #pragma unroll
;         for (int pr = 0; pr < 2; ++pr) { const v2u a = pack4(Oin[2 * pr]), bq = pack4(Oin[2 * pr + 1]); v4u o; o.x = a.x; o.y = a.y; o.z = bq.x; o.w = bq.y; stu<v4u>(pp + pr * 1024, L.pend, o); }
;     } else {
;         f32x4 O[4]; float ss[4] = {0.f, 0.f, 0.f, 0.f};
; #pragma unroll
;         for (int t = 0; t < 4; ++t)
;             { const f32x4 pv = unpack4(f.pend[t]);
; #pragma unroll
;             for (int i = 0; i < 4; ++i) { O[t][i] = Oin[t][i] + pv[i]; ss[i] += O[t][i] * O[t][i]; } }
; #pragma unroll
;         for (int i = 0; i < 4; ++i) ss[i] = frsq(row16_sum(ss[i]) * (1.f / 64.f) + EPS);
;         char* mp = (char*)F.MIX + ((size_t)row0 * 1024 + (GDN ? 0 : 768) + h * 64) * 2;
; #pragma unroll
;         for (int i = 0; i < 4; ++i) { const f32x4 g = unpack4(f.gz[i]); f32x4 ov;
; #pragma unroll
;             for (int t = 0; t < 4; ++t) ov[t] = O[t][i] * ss[i] * g[t];
;             stu<v2u>(upin(mp + i * 2048), L.mix, pack4(ov)); }
.LBB0_520:
	s_cmp_gt_u32 s23, 3
	s_cselect_b32 s5, 39, 3
	s_add_i32 s5, s5, s22
	s_add_i32 s1, s5, 3
	s_and_b64 s[6:7], s[90:91], exec
	s_cselect_b32 s1, s23, s1
	s_cmp_lt_u32 s4, 5
	s_cselect_b32 s3, 2, 20
	s_cmp_lt_u32 s23, s3
	s_mov_b64 s[12:13], -1
	s_cbranch_scc1 .LBB0_522
	s_cmp_lt_i32 s1, 4
	s_cselect_b32 s3, s25, s24
	s_lshl_b32 s6, s1, 6
	s_add_i32 s6, s3, s6
	s_ashr_i32 s7, s6, 31
	s_lshl_b64 s[6:7], s[6:7], 11
	s_add_u32 s18, s26, s6
	s_addc_u32 s19, s27, s7
	s_mov_b64 s[6:7], s[18:19]
	v_lshlrev_b32_e32 v208, 16, v2
	v_and_b32_e32 v209, 0xffff0000, v2
	v_lshlrev_b32_e32 v210, 16, v3
	v_and_b32_e32 v211, 0xffff0000, v3
	v_pk_add_f32 v[212:213], v[130:131], v[208:209]
	v_pk_add_f32 v[214:215], v[132:133], v[210:211]
	v_pk_mul_f32 v[204:205], v[212:213], v[212:213]
	v_pk_mul_f32 v[206:207], v[214:215], v[214:215]
	v_lshlrev_b32_e32 v208, 16, v4
	v_and_b32_e32 v209, 0xffff0000, v4
	v_lshlrev_b32_e32 v210, 16, v5
	v_and_b32_e32 v211, 0xffff0000, v5
	v_pk_add_f32 v[216:217], v[134:135], v[208:209]
	v_pk_add_f32 v[218:219], v[136:137], v[210:211]
	v_pk_fma_f32 v[204:205], v[216:217], v[216:217], v[204:205]
	v_pk_fma_f32 v[206:207], v[218:219], v[218:219], v[206:207]
	v_lshlrev_b32_e32 v208, 16, v6
	v_and_b32_e32 v209, 0xffff0000, v6
	v_lshlrev_b32_e32 v210, 16, v7
	v_and_b32_e32 v211, 0xffff0000, v7
	v_pk_add_f32 v[224:225], v[138:139], v[208:209]
	v_pk_add_f32 v[226:227], v[140:141], v[210:211]
	v_pk_fma_f32 v[204:205], v[224:225], v[224:225], v[204:205]
	v_pk_fma_f32 v[206:207], v[226:227], v[226:227], v[206:207]
	v_lshlrev_b32_e32 v208, 16, v8
	v_and_b32_e32 v209, 0xffff0000, v8
	v_lshlrev_b32_e32 v210, 16, v9
	v_and_b32_e32 v211, 0xffff0000, v9
	v_pk_add_f32 v[242:243], v[142:143], v[208:209]
	v_pk_add_f32 v[244:245], v[144:145], v[210:211]
	v_pk_fma_f32 v[204:205], v[242:243], v[242:243], v[204:205]
	v_pk_fma_f32 v[206:207], v[244:245], v[244:245], v[206:207]
	s_nop 1
	v_add_f32_dpp v204, v204, v204 quad_perm:[1,0,3,2] row_mask:0xf bank_mask:0xf bound_ctrl:1
	v_add_f32_dpp v205, v205, v205 quad_perm:[1,0,3,2] row_mask:0xf bank_mask:0xf bound_ctrl:1
	v_add_f32_dpp v206, v206, v206 quad_perm:[1,0,3,2] row_mask:0xf bank_mask:0xf bound_ctrl:1
	v_add_f32_dpp v207, v207, v207 quad_perm:[1,0,3,2] row_mask:0xf bank_mask:0xf bound_ctrl:1
	v_add_f32_dpp v204, v204, v204 quad_perm:[2,3,0,1] row_mask:0xf bank_mask:0xf bound_ctrl:1
	v_add_f32_dpp v205, v205, v205 quad_perm:[2,3,0,1] row_mask:0xf bank_mask:0xf bound_ctrl:1
	v_add_f32_dpp v206, v206, v206 quad_perm:[2,3,0,1] row_mask:0xf bank_mask:0xf bound_ctrl:1
	v_add_f32_dpp v207, v207, v207 quad_perm:[2,3,0,1] row_mask:0xf bank_mask:0xf bound_ctrl:1
	v_add_f32_dpp v204, v204, v204 row_half_mirror row_mask:0xf bank_mask:0xf bound_ctrl:1
	v_add_f32_dpp v205, v205, v205 row_half_mirror row_mask:0xf bank_mask:0xf bound_ctrl:1
	v_add_f32_dpp v206, v206, v206 row_half_mirror row_mask:0xf bank_mask:0xf bound_ctrl:1
	v_add_f32_dpp v207, v207, v207 row_half_mirror row_mask:0xf bank_mask:0xf bound_ctrl:1
	v_add_f32_dpp v204, v204, v204 row_mirror row_mask:0xf bank_mask:0xf bound_ctrl:1
	v_add_f32_dpp v205, v205, v205 row_mirror row_mask:0xf bank_mask:0xf bound_ctrl:1
	v_add_f32_dpp v206, v206, v206 row_mirror row_mask:0xf bank_mask:0xf bound_ctrl:1
	v_add_f32_dpp v207, v207, v207 row_mirror row_mask:0xf bank_mask:0xf bound_ctrl:1
	v_fmamk_f32 v204, v204, 0x3c800000, v231
	v_fmamk_f32 v205, v205, 0x3c800000, v231
	v_fmamk_f32 v206, v206, 0x3c800000, v231
	v_fmamk_f32 v207, v207, 0x3c800000, v231
	v_rsq_f32_e32 v204, v204
	v_rsq_f32_e32 v205, v205
	v_rsq_f32_e32 v206, v206
	v_rsq_f32_e32 v207, v207
	v_lshlrev_b32_e32 v208, 16, v156
	v_lshlrev_b32_e32 v209, 16, v158
	v_lshlrev_b32_e32 v210, 16, v160
	v_lshlrev_b32_e32 v211, 16, v162
	v_pk_mul_f32 v[212:213], v[212:213], v[204:205]
	v_pk_mul_f32 v[214:215], v[214:215], v[206:207]
	v_pk_mul_f32 v[212:213], v[212:213], v[208:209]
	v_pk_mul_f32 v[214:215], v[214:215], v[210:211]
	v_and_b32_e32 v208, 0xffff0000, v156
	v_and_b32_e32 v209, 0xffff0000, v158
	v_and_b32_e32 v210, 0xffff0000, v160
	v_and_b32_e32 v211, 0xffff0000, v162
	v_pk_mul_f32 v[216:217], v[216:217], v[204:205]
	v_pk_mul_f32 v[218:219], v[218:219], v[206:207]
	v_pk_mul_f32 v[216:217], v[216:217], v[208:209]
	v_pk_mul_f32 v[218:219], v[218:219], v[210:211]
	v_lshlrev_b32_e32 v208, 16, v157
	v_lshlrev_b32_e32 v209, 16, v159
	v_lshlrev_b32_e32 v210, 16, v161
	v_lshlrev_b32_e32 v211, 16, v163
	v_pk_mul_f32 v[224:225], v[224:225], v[204:205]
	v_pk_mul_f32 v[226:227], v[226:227], v[206:207]
	v_pk_mul_f32 v[224:225], v[224:225], v[208:209]
	v_pk_mul_f32 v[226:227], v[226:227], v[210:211]
	v_and_b32_e32 v208, 0xffff0000, v157
	v_and_b32_e32 v209, 0xffff0000, v159
	v_and_b32_e32 v210, 0xffff0000, v161
	v_and_b32_e32 v211, 0xffff0000, v163
	v_pk_mul_f32 v[242:243], v[242:243], v[204:205]
	v_pk_mul_f32 v[244:245], v[244:245], v[206:207]
	v_pk_mul_f32 v[242:243], v[242:243], v[208:209]
	v_pk_mul_f32 v[244:245], v[244:245], v[210:211]
	v_cvt_pk_bf16_f32 v204, v212, v216
	v_cvt_pk_bf16_f32 v205, v224, v242
	v_cvt_pk_bf16_f32 v210, v213, v217
	v_cvt_pk_bf16_f32 v211, v225, v243
	v_cvt_pk_bf16_f32 v206, v214, v218
	v_cvt_pk_bf16_f32 v207, v226, v244
	v_cvt_pk_bf16_f32 v218, v215, v219
	v_cvt_pk_bf16_f32 v219, v227, v245
	v_and_b32_e32 v220, 1, v232
	v_mul_u32_u24_e32 v220, 0x7f8, v220
	v_add_u32_e32 v220, v40, v220
	s_mov_b32 vcc_lo, 0x55555555
	s_mov_b32 vcc_hi, 0x55555555
	v_cndmask_b32_dpp v208, v210, v204, vcc quad_perm:[1,0,3,2] row_mask:0xf bank_mask:0xf
	v_cndmask_b32_dpp v209, v211, v205, vcc quad_perm:[1,0,3,2] row_mask:0xf bank_mask:0xf
	v_cndmask_b32_dpp v216, v218, v206, vcc quad_perm:[1,0,3,2] row_mask:0xf bank_mask:0xf
	v_cndmask_b32_dpp v217, v219, v207, vcc quad_perm:[1,0,3,2] row_mask:0xf bank_mask:0xf
	s_not_b64 vcc, vcc
	v_cndmask_b32_dpp v210, v204, v210, vcc quad_perm:[1,0,3,2] row_mask:0xf bank_mask:0xf
	v_cndmask_b32_dpp v211, v205, v211, vcc quad_perm:[1,0,3,2] row_mask:0xf bank_mask:0xf
	v_cndmask_b32_dpp v218, v206, v218, vcc quad_perm:[1,0,3,2] row_mask:0xf bank_mask:0xf
	v_cndmask_b32_dpp v219, v207, v219, vcc quad_perm:[1,0,3,2] row_mask:0xf bank_mask:0xf
	global_store_dwordx4 v220, v[208:211], s[6:7]
	s_add_u32 s6, s18, 0x800
	s_addc_u32 s7, s19, 0
	s_mov_b64 s[12:13], 0
	s_add_u32 s6, s18, 0x1000
	s_addc_u32 s7, s19, 0
	global_store_dwordx4 v220, v[216:219], s[6:7]
	s_add_u32 s6, s18, 0x1800
	s_addc_u32 s7, s19, 0

; __device__ __forceinline__ float row16_sum(float v) { v += dppf<0xB1>(v); v += dppf<0x4E>(v); v += dppf<0x141>(v); v += dppf<0x140>(v); return v; }
; __device__ __forceinline__ float frsq(float x) { return __builtin_amdgcn_rsqf(x); }
; __device__ __forceinline__ v2u pack4(const f32x4 v) { v2u r; r.x = pk2(v[0], v[1]); r.y = pk2(v[2], v[3]); return r; }
; __device__ __forceinline__ f32x4 unpack4(const v2u w) { f32x4 r; r[0] = bflo(w.x); r[1] = bfhi(w.x); r[2] = bflo(w.y); r[3] = bfhi(w.y); return r; }
; __device__ __forceinline__ const char* upin(const char* p) { asm volatile("" : "+s"(p)); return p; }
; __device__ __forceinline__ char* upin(char* p) { asm volatile("" : "+s"(p)); return p; }
; template <bool GDN> __device__ __forceinline__ void scan_finish(const Frame& F, int b, int h, int dir, const ScanLane& L, int s, float* PEND, const f32x4 (&Oin)[4], const ScanFin& f) {
;     const int cidx = dir ? (s < 4 ? 3 - s : 39 - s) : s; const int row0 = chunk_row0(b, cidx);
;     if (scan_first(s)) {
;         char* pp = upin((char*)PEND + (size_t)((b * 4 + h) * 36 + cidx) * 16384);
; #pragma unroll
;         for (int pr = 0; pr < 2; ++pr) { const v2u a = pack4(Oin[2 * pr]), bq = pack4(Oin[2 * pr + 1]); v4u o; o.x = a.x; o.y = a.y; o.z = bq.x; o.w = bq.y; stu<v4u>(pp + pr * 1024, L.pend, o); }
;     } else {
;         f32x4 O[4]; float ss[4] = {0.f, 0.f, 0.f, 0.f};
; #pragma unroll
;         for (int t = 0; t < 4; ++t)
;             { const f32x4 pv = unpack4(f.pend[t]);
; #pragma unroll
;             for (int i = 0; i < 4; ++i) { O[t][i] = Oin[t][i] + pv[i]; ss[i] += O[t][i] * O[t][i]; } }
; #pragma unroll
;         for (int i = 0; i < 4; ++i) ss[i] = frsq(row16_sum(ss[i]) * (1.f / 64.f) + EPS);
;         char* mp = (char*)F.MIX + ((size_t)row0 * 1024 + (GDN ? 0 : 768) + h * 64) * 2;
; #pragma unroll
;         for (int i = 0; i < 4; ++i) { const f32x4 g = unpack4(f.gz[i]); f32x4 ov;
; #pragma unroll
;             for (int t = 0; t < 4; ++t) ov[t] = O[t][i] * ss[i] * g[t];
;             stu<v2u>(upin(mp + i * 2048), L.mix, pack4(ov)); }
.LBB0_537:
	s_cmp_gt_u32 s23, 2
	s_cselect_b32 s6, 20, 2
	s_cmp_lt_u32 s4, s6
	s_mov_b64 s[10:11], -1
	s_waitcnt lgkmcnt(0)
	s_barrier
	s_cbranch_scc1 .LBB0_540
	s_cmp_lt_i32 s5, 4
	s_cselect_b32 s4, s25, s24
	s_lshl_b32 s6, s5, 6
	s_add_i32 s6, s4, s6
	s_ashr_i32 s7, s6, 31
	s_lshl_b64 s[6:7], s[6:7], 11
	s_add_u32 s10, s26, s6
	s_addc_u32 s11, s27, s7
	s_mov_b64 s[6:7], s[10:11]
	v_lshlrev_b32_e32 v208, 16, v10
	v_and_b32_e32 v209, 0xffff0000, v10
	v_lshlrev_b32_e32 v210, 16, v11
	v_and_b32_e32 v211, 0xffff0000, v11
	v_pk_add_f32 v[212:213], v[130:131], v[208:209]
	v_pk_add_f32 v[214:215], v[132:133], v[210:211]
	v_pk_mul_f32 v[204:205], v[212:213], v[212:213]
	v_pk_mul_f32 v[206:207], v[214:215], v[214:215]
	v_lshlrev_b32_e32 v208, 16, v12
	v_and_b32_e32 v209, 0xffff0000, v12
	v_lshlrev_b32_e32 v210, 16, v13
	v_and_b32_e32 v211, 0xffff0000, v13
	v_pk_add_f32 v[216:217], v[134:135], v[208:209]
	v_pk_add_f32 v[218:219], v[136:137], v[210:211]
	v_pk_fma_f32 v[204:205], v[216:217], v[216:217], v[204:205]
	v_pk_fma_f32 v[206:207], v[218:219], v[218:219], v[206:207]
	v_lshlrev_b32_e32 v208, 16, v14
	v_and_b32_e32 v209, 0xffff0000, v14
	v_lshlrev_b32_e32 v210, 16, v15
	v_and_b32_e32 v211, 0xffff0000, v15
	v_pk_add_f32 v[224:225], v[138:139], v[208:209]
	v_pk_add_f32 v[226:227], v[140:141], v[210:211]
	v_pk_fma_f32 v[204:205], v[224:225], v[224:225], v[204:205]
	v_pk_fma_f32 v[206:207], v[226:227], v[226:227], v[206:207]
	v_lshlrev_b32_e32 v208, 16, v16
	v_and_b32_e32 v209, 0xffff0000, v16
	v_lshlrev_b32_e32 v210, 16, v17
	v_and_b32_e32 v211, 0xffff0000, v17
	v_pk_add_f32 v[242:243], v[142:143], v[208:209]
	v_pk_add_f32 v[244:245], v[144:145], v[210:211]
	v_pk_fma_f32 v[204:205], v[242:243], v[242:243], v[204:205]
	v_pk_fma_f32 v[206:207], v[244:245], v[244:245], v[206:207]
	s_nop 1
	v_add_f32_dpp v204, v204, v204 quad_perm:[1,0,3,2] row_mask:0xf bank_mask:0xf bound_ctrl:1
	v_add_f32_dpp v205, v205, v205 quad_perm:[1,0,3,2] row_mask:0xf bank_mask:0xf bound_ctrl:1
	v_add_f32_dpp v206, v206, v206 quad_perm:[1,0,3,2] row_mask:0xf bank_mask:0xf bound_ctrl:1
	v_add_f32_dpp v207, v207, v207 quad_perm:[1,0,3,2] row_mask:0xf bank_mask:0xf bound_ctrl:1
	v_add_f32_dpp v204, v204, v204 quad_perm:[2,3,0,1] row_mask:0xf bank_mask:0xf bound_ctrl:1
	v_add_f32_dpp v205, v205, v205 quad_perm:[2,3,0,1] row_mask:0xf bank_mask:0xf bound_ctrl:1
	v_add_f32_dpp v206, v206, v206 quad_perm:[2,3,0,1] row_mask:0xf bank_mask:0xf bound_ctrl:1
	v_add_f32_dpp v207, v207, v207 quad_perm:[2,3,0,1] row_mask:0xf bank_mask:0xf bound_ctrl:1
	v_add_f32_dpp v204, v204, v204 row_half_mirror row_mask:0xf bank_mask:0xf bound_ctrl:1
	v_add_f32_dpp v205, v205, v205 row_half_mirror row_mask:0xf bank_mask:0xf bound_ctrl:1
	v_add_f32_dpp v206, v206, v206 row_half_mirror row_mask:0xf bank_mask:0xf bound_ctrl:1
	v_add_f32_dpp v207, v207, v207 row_half_mirror row_mask:0xf bank_mask:0xf bound_ctrl:1
	v_add_f32_dpp v204, v204, v204 row_mirror row_mask:0xf bank_mask:0xf bound_ctrl:1
	v_add_f32_dpp v205, v205, v205 row_mirror row_mask:0xf bank_mask:0xf bound_ctrl:1
	v_add_f32_dpp v206, v206, v206 row_mirror row_mask:0xf bank_mask:0xf bound_ctrl:1
	v_add_f32_dpp v207, v207, v207 row_mirror row_mask:0xf bank_mask:0xf bound_ctrl:1
	v_fmamk_f32 v204, v204, 0x3c800000, v231
	v_fmamk_f32 v205, v205, 0x3c800000, v231
	v_fmamk_f32 v206, v206, 0x3c800000, v231
	v_fmamk_f32 v207, v207, 0x3c800000, v231
	v_rsq_f32_e32 v204, v204
	v_rsq_f32_e32 v205, v205
	v_rsq_f32_e32 v206, v206
	v_rsq_f32_e32 v207, v207
	v_lshlrev_b32_e32 v208, 16, v164
	v_lshlrev_b32_e32 v209, 16, v178
	v_lshlrev_b32_e32 v210, 16, v180
	v_lshlrev_b32_e32 v211, 16, v182
	v_pk_mul_f32 v[212:213], v[212:213], v[204:205]
	v_pk_mul_f32 v[214:215], v[214:215], v[206:207]
	v_pk_mul_f32 v[212:213], v[212:213], v[208:209]
	v_pk_mul_f32 v[214:215], v[214:215], v[210:211]
	v_and_b32_e32 v208, 0xffff0000, v164
	v_and_b32_e32 v209, 0xffff0000, v178
	v_and_b32_e32 v210, 0xffff0000, v180
	v_and_b32_e32 v211, 0xffff0000, v182
	v_pk_mul_f32 v[216:217], v[216:217], v[204:205]
	v_pk_mul_f32 v[218:219], v[218:219], v[206:207]
	v_pk_mul_f32 v[216:217], v[216:217], v[208:209]
	v_pk_mul_f32 v[218:219], v[218:219], v[210:211]
	v_lshlrev_b32_e32 v208, 16, v165
	v_lshlrev_b32_e32 v209, 16, v179
	v_lshlrev_b32_e32 v210, 16, v181
	v_lshlrev_b32_e32 v211, 16, v183
	v_pk_mul_f32 v[224:225], v[224:225], v[204:205]
	v_pk_mul_f32 v[226:227], v[226:227], v[206:207]
	v_pk_mul_f32 v[224:225], v[224:225], v[208:209]
	v_pk_mul_f32 v[226:227], v[226:227], v[210:211]
	v_and_b32_e32 v208, 0xffff0000, v165
	v_and_b32_e32 v209, 0xffff0000, v179
	v_and_b32_e32 v210, 0xffff0000, v181
	v_and_b32_e32 v211, 0xffff0000, v183
	v_pk_mul_f32 v[242:243], v[242:243], v[204:205]
	v_pk_mul_f32 v[244:245], v[244:245], v[206:207]
	v_pk_mul_f32 v[242:243], v[242:243], v[208:209]
	v_pk_mul_f32 v[244:245], v[244:245], v[210:211]
	v_cvt_pk_bf16_f32 v204, v212, v216
	v_cvt_pk_bf16_f32 v205, v224, v242
	v_cvt_pk_bf16_f32 v210, v213, v217
	v_cvt_pk_bf16_f32 v211, v225, v243
	v_cvt_pk_bf16_f32 v206, v214, v218
	v_cvt_pk_bf16_f32 v207, v226, v244
	v_cvt_pk_bf16_f32 v218, v215, v219
	v_cvt_pk_bf16_f32 v219, v227, v245
	v_and_b32_e32 v220, 1, v232
	v_mul_u32_u24_e32 v220, 0x7f8, v220
	v_add_u32_e32 v220, v146, v220
	s_mov_b32 vcc_lo, 0x55555555
	s_mov_b32 vcc_hi, 0x55555555
	v_cndmask_b32_dpp v208, v210, v204, vcc quad_perm:[1,0,3,2] row_mask:0xf bank_mask:0xf
	v_cndmask_b32_dpp v209, v211, v205, vcc quad_perm:[1,0,3,2] row_mask:0xf bank_mask:0xf
	v_cndmask_b32_dpp v216, v218, v206, vcc quad_perm:[1,0,3,2] row_mask:0xf bank_mask:0xf
	v_cndmask_b32_dpp v217, v219, v207, vcc quad_perm:[1,0,3,2] row_mask:0xf bank_mask:0xf
	s_not_b64 vcc, vcc
	v_cndmask_b32_dpp v210, v204, v210, vcc quad_perm:[1,0,3,2] row_mask:0xf bank_mask:0xf
	v_cndmask_b32_dpp v211, v205, v211, vcc quad_perm:[1,0,3,2] row_mask:0xf bank_mask:0xf
	v_cndmask_b32_dpp v218, v206, v218, vcc quad_perm:[1,0,3,2] row_mask:0xf bank_mask:0xf
	v_cndmask_b32_dpp v219, v207, v219, vcc quad_perm:[1,0,3,2] row_mask:0xf bank_mask:0xf
	global_store_dwordx4 v220, v[208:211], s[6:7]
	s_add_u32 s6, s10, 0x800
	s_addc_u32 s7, s11, 0
	s_add_u32 s6, s10, 0x1000
	s_addc_u32 s7, s11, 0
	global_store_dwordx4 v220, v[216:219], s[6:7]
	s_add_u32 s6, s10, 0x1800
	s_addc_u32 s7, s11, 0
	s_cbranch_execz .LBB0_541

; __device__ __forceinline__ float row16_sum(float v) { v += dppf<0xB1>(v); v += dppf<0x4E>(v); v += dppf<0x141>(v); v += dppf<0x140>(v); return v; }
; __device__ __forceinline__ float frsq(float x) { return __builtin_amdgcn_rsqf(x); }
; __device__ __forceinline__ v2u pack4(const f32x4 v) { v2u r; r.x = pk2(v[0], v[1]); r.y = pk2(v[2], v[3]); return r; }
; __device__ __forceinline__ f32x4 unpack4(const v2u w) { f32x4 r; r[0] = bflo(w.x); r[1] = bfhi(w.x); r[2] = bflo(w.y); r[3] = bfhi(w.y); return r; }
; __device__ __forceinline__ const char* upin(const char* p) { asm volatile("" : "+s"(p)); return p; }
; __device__ __forceinline__ char* upin(char* p) { asm volatile("" : "+s"(p)); return p; }
; template <bool GDN> __device__ __forceinline__ void scan_finish(const Frame& F, int b, int h, int dir, const ScanLane& L, int s, float* PEND, const f32x4 (&Oin)[4], const ScanFin& f) {
;     ...
;         f32x4 O[4]; float ss[4] = {0.f, 0.f, 0.f, 0.f};
; #pragma unroll
;         for (int t = 0; t < 4; ++t)
;             { const f32x4 pv = unpack4(f.pend[t]);
; #pragma unroll
;             for (int i = 0; i < 4; ++i) { O[t][i] = Oin[t][i] + pv[i]; ss[i] += O[t][i] * O[t][i]; } }
; #pragma unroll
;         for (int i = 0; i < 4; ++i) ss[i] = frsq(row16_sum(ss[i]) * (1.f / 64.f) + EPS);
;         char* mp = (char*)F.MIX + ((size_t)row0 * 1024 + (GDN ? 0 : 768) + h * 64) * 2;
; #pragma unroll
;         for (int i = 0; i < 4; ++i) { const f32x4 g = unpack4(f.gz[i]); f32x4 ov;
; #pragma unroll
;             for (int t = 0; t < 4; ++t) ov[t] = O[t][i] * ss[i] * g[t];
;             stu<v2u>(upin(mp + i * 2048), L.mix, pack4(ov)); }
.LBB0_568:
	s_cmp_lt_i32 s4, 4
	s_cselect_b32 s3, s25, s24
	s_lshl_b32 s5, s4, 6
	s_add_i32 s6, s3, s5
	s_ashr_i32 s7, s6, 31
	s_lshl_b64 s[6:7], s[6:7], 11
	s_add_u32 s10, s26, s6
	s_addc_u32 s11, s27, s7
	s_mov_b64 s[6:7], s[10:11]
	v_lshlrev_b32_e32 v208, 16, v2
	v_and_b32_e32 v209, 0xffff0000, v2
	v_lshlrev_b32_e32 v210, 16, v3
	v_and_b32_e32 v211, 0xffff0000, v3
	v_pk_add_f32 v[212:213], v[130:131], v[208:209]
	v_pk_add_f32 v[214:215], v[132:133], v[210:211]
	v_pk_mul_f32 v[204:205], v[212:213], v[212:213]
	v_pk_mul_f32 v[206:207], v[214:215], v[214:215]
	v_lshlrev_b32_e32 v208, 16, v4
	v_and_b32_e32 v209, 0xffff0000, v4
	v_lshlrev_b32_e32 v210, 16, v5
	v_and_b32_e32 v211, 0xffff0000, v5
	v_pk_add_f32 v[216:217], v[134:135], v[208:209]
	v_pk_add_f32 v[218:219], v[136:137], v[210:211]
	v_pk_fma_f32 v[204:205], v[216:217], v[216:217], v[204:205]
	v_pk_fma_f32 v[206:207], v[218:219], v[218:219], v[206:207]
	v_lshlrev_b32_e32 v208, 16, v6
	v_and_b32_e32 v209, 0xffff0000, v6
	v_lshlrev_b32_e32 v210, 16, v7
	v_and_b32_e32 v211, 0xffff0000, v7
	v_pk_add_f32 v[224:225], v[138:139], v[208:209]
	v_pk_add_f32 v[226:227], v[140:141], v[210:211]
	v_pk_fma_f32 v[204:205], v[224:225], v[224:225], v[204:205]
	v_pk_fma_f32 v[206:207], v[226:227], v[226:227], v[206:207]
	v_lshlrev_b32_e32 v208, 16, v8
	v_and_b32_e32 v209, 0xffff0000, v8
	v_lshlrev_b32_e32 v210, 16, v9
	v_and_b32_e32 v211, 0xffff0000, v9
	v_pk_add_f32 v[242:243], v[142:143], v[208:209]
	v_pk_add_f32 v[244:245], v[144:145], v[210:211]
	v_pk_fma_f32 v[204:205], v[242:243], v[242:243], v[204:205]
	v_pk_fma_f32 v[206:207], v[244:245], v[244:245], v[206:207]
	s_nop 1
	v_add_f32_dpp v204, v204, v204 quad_perm:[1,0,3,2] row_mask:0xf bank_mask:0xf bound_ctrl:1
	v_add_f32_dpp v205, v205, v205 quad_perm:[1,0,3,2] row_mask:0xf bank_mask:0xf bound_ctrl:1
	v_add_f32_dpp v206, v206, v206 quad_perm:[1,0,3,2] row_mask:0xf bank_mask:0xf bound_ctrl:1
	v_add_f32_dpp v207, v207, v207 quad_perm:[1,0,3,2] row_mask:0xf bank_mask:0xf bound_ctrl:1
	v_add_f32_dpp v204, v204, v204 quad_perm:[2,3,0,1] row_mask:0xf bank_mask:0xf bound_ctrl:1
	v_add_f32_dpp v205, v205, v205 quad_perm:[2,3,0,1] row_mask:0xf bank_mask:0xf bound_ctrl:1
	v_add_f32_dpp v206, v206, v206 quad_perm:[2,3,0,1] row_mask:0xf bank_mask:0xf bound_ctrl:1
	v_add_f32_dpp v207, v207, v207 quad_perm:[2,3,0,1] row_mask:0xf bank_mask:0xf bound_ctrl:1
	v_add_f32_dpp v204, v204, v204 row_half_mirror row_mask:0xf bank_mask:0xf bound_ctrl:1
	v_add_f32_dpp v205, v205, v205 row_half_mirror row_mask:0xf bank_mask:0xf bound_ctrl:1
	v_add_f32_dpp v206, v206, v206 row_half_mirror row_mask:0xf bank_mask:0xf bound_ctrl:1
	v_add_f32_dpp v207, v207, v207 row_half_mirror row_mask:0xf bank_mask:0xf bound_ctrl:1
	v_add_f32_dpp v204, v204, v204 row_mirror row_mask:0xf bank_mask:0xf bound_ctrl:1
	v_add_f32_dpp v205, v205, v205 row_mirror row_mask:0xf bank_mask:0xf bound_ctrl:1
	v_add_f32_dpp v206, v206, v206 row_mirror row_mask:0xf bank_mask:0xf bound_ctrl:1
	v_add_f32_dpp v207, v207, v207 row_mirror row_mask:0xf bank_mask:0xf bound_ctrl:1
	v_fmamk_f32 v204, v204, 0x3c800000, v231
	v_fmamk_f32 v205, v205, 0x3c800000, v231
	v_fmamk_f32 v206, v206, 0x3c800000, v231
	v_fmamk_f32 v207, v207, 0x3c800000, v231
	v_rsq_f32_e32 v204, v204
	v_rsq_f32_e32 v205, v205
	v_rsq_f32_e32 v206, v206
	v_rsq_f32_e32 v207, v207
	v_lshlrev_b32_e32 v208, 16, v156
	v_lshlrev_b32_e32 v209, 16, v158
	v_lshlrev_b32_e32 v210, 16, v160
	v_lshlrev_b32_e32 v211, 16, v162
	v_pk_mul_f32 v[212:213], v[212:213], v[204:205]
	v_pk_mul_f32 v[214:215], v[214:215], v[206:207]
	v_pk_mul_f32 v[212:213], v[212:213], v[208:209]
	v_pk_mul_f32 v[214:215], v[214:215], v[210:211]
	v_and_b32_e32 v208, 0xffff0000, v156
	v_and_b32_e32 v209, 0xffff0000, v158
	v_and_b32_e32 v210, 0xffff0000, v160
	v_and_b32_e32 v211, 0xffff0000, v162
	v_pk_mul_f32 v[216:217], v[216:217], v[204:205]
	v_pk_mul_f32 v[218:219], v[218:219], v[206:207]
	v_pk_mul_f32 v[216:217], v[216:217], v[208:209]
	v_pk_mul_f32 v[218:219], v[218:219], v[210:211]
	v_lshlrev_b32_e32 v208, 16, v157
	v_lshlrev_b32_e32 v209, 16, v159
	v_lshlrev_b32_e32 v210, 16, v161
	v_lshlrev_b32_e32 v211, 16, v163
	v_pk_mul_f32 v[224:225], v[224:225], v[204:205]
	v_pk_mul_f32 v[226:227], v[226:227], v[206:207]
	v_pk_mul_f32 v[224:225], v[224:225], v[208:209]
	v_pk_mul_f32 v[226:227], v[226:227], v[210:211]
	v_and_b32_e32 v208, 0xffff0000, v157
	v_and_b32_e32 v209, 0xffff0000, v159
	v_and_b32_e32 v210, 0xffff0000, v161
	v_and_b32_e32 v211, 0xffff0000, v163
	v_pk_mul_f32 v[242:243], v[242:243], v[204:205]
	v_pk_mul_f32 v[244:245], v[244:245], v[206:207]
	v_pk_mul_f32 v[242:243], v[242:243], v[208:209]
	v_pk_mul_f32 v[244:245], v[244:245], v[210:211]
	v_cvt_pk_bf16_f32 v204, v212, v216
	v_cvt_pk_bf16_f32 v205, v224, v242
	v_cvt_pk_bf16_f32 v210, v213, v217
	v_cvt_pk_bf16_f32 v211, v225, v243
	v_cvt_pk_bf16_f32 v206, v214, v218
	v_cvt_pk_bf16_f32 v207, v226, v244
	v_cvt_pk_bf16_f32 v218, v215, v219
	v_cvt_pk_bf16_f32 v219, v227, v245
	v_and_b32_e32 v220, 1, v232
	v_mul_u32_u24_e32 v220, 0x7f8, v220
	v_add_u32_e32 v220, v28, v220
	s_mov_b32 vcc_lo, 0x55555555
	s_mov_b32 vcc_hi, 0x55555555
	v_cndmask_b32_dpp v208, v210, v204, vcc quad_perm:[1,0,3,2] row_mask:0xf bank_mask:0xf
	v_cndmask_b32_dpp v209, v211, v205, vcc quad_perm:[1,0,3,2] row_mask:0xf bank_mask:0xf
	v_cndmask_b32_dpp v216, v218, v206, vcc quad_perm:[1,0,3,2] row_mask:0xf bank_mask:0xf
	v_cndmask_b32_dpp v217, v219, v207, vcc quad_perm:[1,0,3,2] row_mask:0xf bank_mask:0xf
	s_not_b64 vcc, vcc
	v_cndmask_b32_dpp v210, v204, v210, vcc quad_perm:[1,0,3,2] row_mask:0xf bank_mask:0xf
	v_cndmask_b32_dpp v211, v205, v211, vcc quad_perm:[1,0,3,2] row_mask:0xf bank_mask:0xf
	v_cndmask_b32_dpp v218, v206, v218, vcc quad_perm:[1,0,3,2] row_mask:0xf bank_mask:0xf
	v_cndmask_b32_dpp v219, v207, v219, vcc quad_perm:[1,0,3,2] row_mask:0xf bank_mask:0xf
	global_store_dwordx4 v220, v[208:211], s[6:7]
	s_add_u32 s6, s10, 0x800
	s_addc_u32 s7, s11, 0
	s_add_u32 s6, s10, 0x1000
	s_addc_u32 s7, s11, 0
	global_store_dwordx4 v220, v[216:219], s[6:7]
	s_add_u32 s6, s10, 0x1800
	s_addc_u32 s7, s11, 0
	s_cbranch_execz .LBB0_581

; __device__ __forceinline__ float row16_sum(float v) { v += dppf<0xB1>(v); v += dppf<0x4E>(v); v += dppf<0x141>(v); v += dppf<0x140>(v); return v; }
; __device__ __forceinline__ float frsq(float x) { return __builtin_amdgcn_rsqf(x); }
; __device__ __forceinline__ v2u pack4(const f32x4 v) { v2u r; r.x = pk2(v[0], v[1]); r.y = pk2(v[2], v[3]); return r; }
; __device__ __forceinline__ f32x4 unpack4(const v2u w) { f32x4 r; r[0] = bflo(w.x); r[1] = bfhi(w.x); r[2] = bflo(w.y); r[3] = bfhi(w.y); return r; }
; __device__ __forceinline__ const char* upin(const char* p) { asm volatile("" : "+s"(p)); return p; }
; __device__ __forceinline__ char* upin(char* p) { asm volatile("" : "+s"(p)); return p; }
; template <bool GDN> __device__ __forceinline__ void scan_finish(const Frame& F, int b, int h, int dir, const ScanLane& L, int s, float* PEND, const f32x4 (&Oin)[4], const ScanFin& f) {
;     const int cidx = dir ? (s < 4 ? 3 - s : 39 - s) : s; const int row0 = chunk_row0(b, cidx);
;     if (scan_first(s)) {
;         char* pp = upin((char*)PEND + (size_t)((b * 4 + h) * 36 + cidx) * 16384);
; #pragma unroll
;         for (int pr = 0; pr < 2; ++pr) { const v2u a = pack4(Oin[2 * pr]), bq = pack4(Oin[2 * pr + 1]); v4u o; o.x = a.x; o.y = a.y; o.z = bq.x; o.w = bq.y; stu<v4u>(pp + pr * 1024, L.pend, o); }
;     } else {
;         f32x4 O[4]; float ss[4] = {0.f, 0.f, 0.f, 0.f};
; #pragma unroll
;         for (int t = 0; t < 4; ++t)
;             { const f32x4 pv = unpack4(f.pend[t]);
; #pragma unroll
;             for (int i = 0; i < 4; ++i) { O[t][i] = Oin[t][i] + pv[i]; ss[i] += O[t][i] * O[t][i]; } }
; #pragma unroll
;         for (int i = 0; i < 4; ++i) ss[i] = frsq(row16_sum(ss[i]) * (1.f / 64.f) + EPS);
;         char* mp = (char*)F.MIX + ((size_t)row0 * 1024 + (GDN ? 0 : 768) + h * 64) * 2;
; #pragma unroll
;         for (int i = 0; i < 4; ++i) { const f32x4 g = unpack4(f.gz[i]); f32x4 ov;
; #pragma unroll
;             for (int t = 0; t < 4; ++t) ov[t] = O[t][i] * ss[i] * g[t];
;             stu<v2u>(upin(mp + i * 2048), L.mix, pack4(ov)); }
.LBB0_575:
	s_cmp_lt_u32 s0, 16
	s_mov_b64 s[10:11], -1
	s_waitcnt lgkmcnt(0)
	s_barrier
	s_cbranch_scc1 .LBB0_584
	s_cmp_lt_i32 s1, 4
	s_cselect_b32 s0, s25, s24
	s_lshl_b32 s4, s1, 6
	s_add_i32 s4, s0, s4
	s_ashr_i32 s5, s4, 31
	s_lshl_b64 s[4:5], s[4:5], 11
	s_add_u32 s10, s26, s4
	s_addc_u32 s11, s27, s5
	s_mov_b64 s[4:5], s[10:11]
	v_lshlrev_b32_e32 v208, 16, v10
	v_and_b32_e32 v209, 0xffff0000, v10
	v_lshlrev_b32_e32 v210, 16, v11
	v_and_b32_e32 v211, 0xffff0000, v11
	v_pk_add_f32 v[212:213], v[130:131], v[208:209]
	v_pk_add_f32 v[214:215], v[132:133], v[210:211]
	v_pk_mul_f32 v[204:205], v[212:213], v[212:213]
	v_pk_mul_f32 v[206:207], v[214:215], v[214:215]
	v_lshlrev_b32_e32 v208, 16, v12
	v_and_b32_e32 v209, 0xffff0000, v12
	v_lshlrev_b32_e32 v210, 16, v13
	v_and_b32_e32 v211, 0xffff0000, v13
	v_pk_add_f32 v[216:217], v[134:135], v[208:209]
	v_pk_add_f32 v[218:219], v[136:137], v[210:211]
	v_pk_fma_f32 v[204:205], v[216:217], v[216:217], v[204:205]
	v_pk_fma_f32 v[206:207], v[218:219], v[218:219], v[206:207]
	v_lshlrev_b32_e32 v208, 16, v14
	v_and_b32_e32 v209, 0xffff0000, v14
	v_lshlrev_b32_e32 v210, 16, v15
	v_and_b32_e32 v211, 0xffff0000, v15
	v_pk_add_f32 v[224:225], v[138:139], v[208:209]
	v_pk_add_f32 v[226:227], v[140:141], v[210:211]
	v_pk_fma_f32 v[204:205], v[224:225], v[224:225], v[204:205]
	v_pk_fma_f32 v[206:207], v[226:227], v[226:227], v[206:207]
	v_lshlrev_b32_e32 v208, 16, v16
	v_and_b32_e32 v209, 0xffff0000, v16
	v_lshlrev_b32_e32 v210, 16, v17
	v_and_b32_e32 v211, 0xffff0000, v17
	v_pk_add_f32 v[242:243], v[142:143], v[208:209]
	v_pk_add_f32 v[244:245], v[144:145], v[210:211]
	v_pk_fma_f32 v[204:205], v[242:243], v[242:243], v[204:205]
	v_pk_fma_f32 v[206:207], v[244:245], v[244:245], v[206:207]
	s_nop 1
	v_add_f32_dpp v204, v204, v204 quad_perm:[1,0,3,2] row_mask:0xf bank_mask:0xf bound_ctrl:1
	v_add_f32_dpp v205, v205, v205 quad_perm:[1,0,3,2] row_mask:0xf bank_mask:0xf bound_ctrl:1
	v_add_f32_dpp v206, v206, v206 quad_perm:[1,0,3,2] row_mask:0xf bank_mask:0xf bound_ctrl:1
	v_add_f32_dpp v207, v207, v207 quad_perm:[1,0,3,2] row_mask:0xf bank_mask:0xf bound_ctrl:1
	v_add_f32_dpp v204, v204, v204 quad_perm:[2,3,0,1] row_mask:0xf bank_mask:0xf bound_ctrl:1
	v_add_f32_dpp v205, v205, v205 quad_perm:[2,3,0,1] row_mask:0xf bank_mask:0xf bound_ctrl:1
	v_add_f32_dpp v206, v206, v206 quad_perm:[2,3,0,1] row_mask:0xf bank_mask:0xf bound_ctrl:1
	v_add_f32_dpp v207, v207, v207 quad_perm:[2,3,0,1] row_mask:0xf bank_mask:0xf bound_ctrl:1
	v_add_f32_dpp v204, v204, v204 row_half_mirror row_mask:0xf bank_mask:0xf bound_ctrl:1
	v_add_f32_dpp v205, v205, v205 row_half_mirror row_mask:0xf bank_mask:0xf bound_ctrl:1
	v_add_f32_dpp v206, v206, v206 row_half_mirror row_mask:0xf bank_mask:0xf bound_ctrl:1
	v_add_f32_dpp v207, v207, v207 row_half_mirror row_mask:0xf bank_mask:0xf bound_ctrl:1
	v_add_f32_dpp v204, v204, v204 row_mirror row_mask:0xf bank_mask:0xf bound_ctrl:1
	v_add_f32_dpp v205, v205, v205 row_mirror row_mask:0xf bank_mask:0xf bound_ctrl:1
	v_add_f32_dpp v206, v206, v206 row_mirror row_mask:0xf bank_mask:0xf bound_ctrl:1
	v_add_f32_dpp v207, v207, v207 row_mirror row_mask:0xf bank_mask:0xf bound_ctrl:1
	v_fmamk_f32 v204, v204, 0x3c800000, v231
	v_fmamk_f32 v205, v205, 0x3c800000, v231
	v_fmamk_f32 v206, v206, 0x3c800000, v231
	v_fmamk_f32 v207, v207, 0x3c800000, v231
	v_rsq_f32_e32 v204, v204
	v_rsq_f32_e32 v205, v205
	v_rsq_f32_e32 v206, v206
	v_rsq_f32_e32 v207, v207
	v_lshlrev_b32_e32 v208, 16, v164
	v_lshlrev_b32_e32 v209, 16, v178
	v_lshlrev_b32_e32 v210, 16, v180
	v_lshlrev_b32_e32 v211, 16, v182
	v_pk_mul_f32 v[212:213], v[212:213], v[204:205]
	v_pk_mul_f32 v[214:215], v[214:215], v[206:207]
	v_pk_mul_f32 v[212:213], v[212:213], v[208:209]
	v_pk_mul_f32 v[214:215], v[214:215], v[210:211]
	v_and_b32_e32 v208, 0xffff0000, v164
	v_and_b32_e32 v209, 0xffff0000, v178
	v_and_b32_e32 v210, 0xffff0000, v180
	v_and_b32_e32 v211, 0xffff0000, v182
	v_pk_mul_f32 v[216:217], v[216:217], v[204:205]
	v_pk_mul_f32 v[218:219], v[218:219], v[206:207]
	v_pk_mul_f32 v[216:217], v[216:217], v[208:209]
	v_pk_mul_f32 v[218:219], v[218:219], v[210:211]
	v_lshlrev_b32_e32 v208, 16, v165
	v_lshlrev_b32_e32 v209, 16, v179
	v_lshlrev_b32_e32 v210, 16, v181
	v_lshlrev_b32_e32 v211, 16, v183
	v_pk_mul_f32 v[224:225], v[224:225], v[204:205]
	v_pk_mul_f32 v[226:227], v[226:227], v[206:207]
	v_pk_mul_f32 v[224:225], v[224:225], v[208:209]
	v_pk_mul_f32 v[226:227], v[226:227], v[210:211]
	v_and_b32_e32 v208, 0xffff0000, v165
	v_and_b32_e32 v209, 0xffff0000, v179
	v_and_b32_e32 v210, 0xffff0000, v181
	v_and_b32_e32 v211, 0xffff0000, v183
	v_pk_mul_f32 v[242:243], v[242:243], v[204:205]
	v_pk_mul_f32 v[244:245], v[244:245], v[206:207]
	v_pk_mul_f32 v[242:243], v[242:243], v[208:209]
	v_pk_mul_f32 v[244:245], v[244:245], v[210:211]
	v_cvt_pk_bf16_f32 v204, v212, v216
	v_cvt_pk_bf16_f32 v205, v224, v242
	v_cvt_pk_bf16_f32 v210, v213, v217
	v_cvt_pk_bf16_f32 v211, v225, v243
	v_cvt_pk_bf16_f32 v206, v214, v218
	v_cvt_pk_bf16_f32 v207, v226, v244
	v_cvt_pk_bf16_f32 v218, v215, v219
	v_cvt_pk_bf16_f32 v219, v227, v245
	v_and_b32_e32 v220, 1, v232
	v_mul_u32_u24_e32 v220, 0x7f8, v220
	v_add_u32_e32 v220, v149, v220
	s_mov_b32 vcc_lo, 0x55555555
	s_mov_b32 vcc_hi, 0x55555555
	v_cndmask_b32_dpp v208, v210, v204, vcc quad_perm:[1,0,3,2] row_mask:0xf bank_mask:0xf
	v_cndmask_b32_dpp v209, v211, v205, vcc quad_perm:[1,0,3,2] row_mask:0xf bank_mask:0xf
	v_cndmask_b32_dpp v216, v218, v206, vcc quad_perm:[1,0,3,2] row_mask:0xf bank_mask:0xf
	v_cndmask_b32_dpp v217, v219, v207, vcc quad_perm:[1,0,3,2] row_mask:0xf bank_mask:0xf
	s_not_b64 vcc, vcc
	v_cndmask_b32_dpp v210, v204, v210, vcc quad_perm:[1,0,3,2] row_mask:0xf bank_mask:0xf
	v_cndmask_b32_dpp v211, v205, v211, vcc quad_perm:[1,0,3,2] row_mask:0xf bank_mask:0xf
	v_cndmask_b32_dpp v218, v206, v218, vcc quad_perm:[1,0,3,2] row_mask:0xf bank_mask:0xf
	v_cndmask_b32_dpp v219, v207, v219, vcc quad_perm:[1,0,3,2] row_mask:0xf bank_mask:0xf
	global_store_dwordx4 v220, v[208:211], s[4:5]
	s_add_u32 s4, s10, 0x800
	s_addc_u32 s5, s11, 0
	s_add_u32 s4, s10, 0x1000
	s_addc_u32 s5, s11, 0
	global_store_dwordx4 v220, v[216:219], s[4:5]
	s_add_u32 s4, s10, 0x1800
	s_addc_u32 s5, s11, 0
	s_cbranch_execz .LBB0_585

; __device__ __forceinline__ float row16_sum(float v) { v += dppf<0xB1>(v); v += dppf<0x4E>(v); v += dppf<0x141>(v); v += dppf<0x140>(v); return v; }
; __device__ __forceinline__ float frsq(float x) { return __builtin_amdgcn_rsqf(x); }
; __device__ __forceinline__ v2u pack4(const f32x4 v) { v2u r; r.x = pk2(v[0], v[1]); r.y = pk2(v[2], v[3]); return r; }
; __device__ __forceinline__ f32x4 unpack4(const v2u w) { f32x4 r; r[0] = bflo(w.x); r[1] = bfhi(w.x); r[2] = bflo(w.y); r[3] = bfhi(w.y); return r; }
; __device__ __forceinline__ const char* upin(const char* p) { asm volatile("" : "+s"(p)); return p; }
; __device__ __forceinline__ char* upin(char* p) { asm volatile("" : "+s"(p)); return p; }
; template <bool GDN> __device__ __forceinline__ void scan_finish(const Frame& F, int b, int h, int dir, const ScanLane& L, int s, float* PEND, const f32x4 (&Oin)[4], const ScanFin& f) {
;     ...
;         f32x4 O[4]; float ss[4] = {0.f, 0.f, 0.f, 0.f};
; #pragma unroll
;         for (int t = 0; t < 4; ++t)
;             { const f32x4 pv = unpack4(f.pend[t]);
; #pragma unroll
;             for (int i = 0; i < 4; ++i) { O[t][i] = Oin[t][i] + pv[i]; ss[i] += O[t][i] * O[t][i]; } }
; #pragma unroll
;         for (int i = 0; i < 4; ++i) ss[i] = frsq(row16_sum(ss[i]) * (1.f / 64.f) + EPS);
;         char* mp = (char*)F.MIX + ((size_t)row0 * 1024 + (GDN ? 0 : 768) + h * 64) * 2;
; #pragma unroll
;         for (int i = 0; i < 4; ++i) { const f32x4 g = unpack4(f.gz[i]); f32x4 ov;
; #pragma unroll
;             for (int t = 0; t < 4; ++t) ov[t] = O[t][i] * ss[i] * g[t];
;             stu<v2u>(upin(mp + i * 2048), L.mix, pack4(ov)); }
.LBB0_602:
	s_cmp_lt_i32 s0, 4
	s_cselect_b32 s1, s25, s24
	s_lshl_b32 s3, s0, 6
	s_add_i32 s4, s1, s3
	s_ashr_i32 s5, s4, 31
	s_lshl_b64 s[4:5], s[4:5], 11
	s_add_u32 s10, s26, s4
	s_addc_u32 s11, s27, s5
	s_mov_b64 s[4:5], s[10:11]
	v_lshlrev_b32_e32 v208, 16, v2
	v_and_b32_e32 v209, 0xffff0000, v2
	v_lshlrev_b32_e32 v210, 16, v3
	v_and_b32_e32 v211, 0xffff0000, v3
	v_pk_add_f32 v[212:213], v[130:131], v[208:209]
	v_pk_add_f32 v[214:215], v[132:133], v[210:211]
	v_pk_mul_f32 v[204:205], v[212:213], v[212:213]
	v_pk_mul_f32 v[206:207], v[214:215], v[214:215]
	v_lshlrev_b32_e32 v208, 16, v4
	v_and_b32_e32 v209, 0xffff0000, v4
	v_lshlrev_b32_e32 v210, 16, v5
	v_and_b32_e32 v211, 0xffff0000, v5
	v_pk_add_f32 v[216:217], v[134:135], v[208:209]
	v_pk_add_f32 v[218:219], v[136:137], v[210:211]
	v_pk_fma_f32 v[204:205], v[216:217], v[216:217], v[204:205]
	v_pk_fma_f32 v[206:207], v[218:219], v[218:219], v[206:207]
	v_lshlrev_b32_e32 v208, 16, v6
	v_and_b32_e32 v209, 0xffff0000, v6
	v_lshlrev_b32_e32 v210, 16, v7
	v_and_b32_e32 v211, 0xffff0000, v7
	v_pk_add_f32 v[224:225], v[138:139], v[208:209]
	v_pk_add_f32 v[226:227], v[140:141], v[210:211]
	v_pk_fma_f32 v[204:205], v[224:225], v[224:225], v[204:205]
	v_pk_fma_f32 v[206:207], v[226:227], v[226:227], v[206:207]
	v_lshlrev_b32_e32 v208, 16, v8
	v_and_b32_e32 v209, 0xffff0000, v8
	v_lshlrev_b32_e32 v210, 16, v9
	v_and_b32_e32 v211, 0xffff0000, v9
	v_pk_add_f32 v[242:243], v[142:143], v[208:209]
	v_pk_add_f32 v[244:245], v[144:145], v[210:211]
	v_pk_fma_f32 v[204:205], v[242:243], v[242:243], v[204:205]
	v_pk_fma_f32 v[206:207], v[244:245], v[244:245], v[206:207]
	s_nop 1
	v_add_f32_dpp v204, v204, v204 quad_perm:[1,0,3,2] row_mask:0xf bank_mask:0xf bound_ctrl:1
	v_add_f32_dpp v205, v205, v205 quad_perm:[1,0,3,2] row_mask:0xf bank_mask:0xf bound_ctrl:1
	v_add_f32_dpp v206, v206, v206 quad_perm:[1,0,3,2] row_mask:0xf bank_mask:0xf bound_ctrl:1
	v_add_f32_dpp v207, v207, v207 quad_perm:[1,0,3,2] row_mask:0xf bank_mask:0xf bound_ctrl:1
	v_add_f32_dpp v204, v204, v204 quad_perm:[2,3,0,1] row_mask:0xf bank_mask:0xf bound_ctrl:1
	v_add_f32_dpp v205, v205, v205 quad_perm:[2,3,0,1] row_mask:0xf bank_mask:0xf bound_ctrl:1
	v_add_f32_dpp v206, v206, v206 quad_perm:[2,3,0,1] row_mask:0xf bank_mask:0xf bound_ctrl:1
	v_add_f32_dpp v207, v207, v207 quad_perm:[2,3,0,1] row_mask:0xf bank_mask:0xf bound_ctrl:1
	v_add_f32_dpp v204, v204, v204 row_half_mirror row_mask:0xf bank_mask:0xf bound_ctrl:1
	v_add_f32_dpp v205, v205, v205 row_half_mirror row_mask:0xf bank_mask:0xf bound_ctrl:1
	v_add_f32_dpp v206, v206, v206 row_half_mirror row_mask:0xf bank_mask:0xf bound_ctrl:1
	v_add_f32_dpp v207, v207, v207 row_half_mirror row_mask:0xf bank_mask:0xf bound_ctrl:1
	v_add_f32_dpp v204, v204, v204 row_mirror row_mask:0xf bank_mask:0xf bound_ctrl:1
	v_add_f32_dpp v205, v205, v205 row_mirror row_mask:0xf bank_mask:0xf bound_ctrl:1
	v_add_f32_dpp v206, v206, v206 row_mirror row_mask:0xf bank_mask:0xf bound_ctrl:1
	v_add_f32_dpp v207, v207, v207 row_mirror row_mask:0xf bank_mask:0xf bound_ctrl:1
	v_fmamk_f32 v204, v204, 0x3c800000, v231
	v_fmamk_f32 v205, v205, 0x3c800000, v231
	v_fmamk_f32 v206, v206, 0x3c800000, v231
	v_fmamk_f32 v207, v207, 0x3c800000, v231
	v_rsq_f32_e32 v204, v204
	v_rsq_f32_e32 v205, v205
	v_rsq_f32_e32 v206, v206
	v_rsq_f32_e32 v207, v207
	v_lshlrev_b32_e32 v208, 16, v156
	v_lshlrev_b32_e32 v209, 16, v158
	v_lshlrev_b32_e32 v210, 16, v160
	v_lshlrev_b32_e32 v211, 16, v162
	v_pk_mul_f32 v[212:213], v[212:213], v[204:205]
	v_pk_mul_f32 v[214:215], v[214:215], v[206:207]
	v_pk_mul_f32 v[212:213], v[212:213], v[208:209]
	v_pk_mul_f32 v[214:215], v[214:215], v[210:211]
	v_and_b32_e32 v208, 0xffff0000, v156
	v_and_b32_e32 v209, 0xffff0000, v158
	v_and_b32_e32 v210, 0xffff0000, v160
	v_and_b32_e32 v211, 0xffff0000, v162
	v_pk_mul_f32 v[216:217], v[216:217], v[204:205]
	v_pk_mul_f32 v[218:219], v[218:219], v[206:207]
	v_pk_mul_f32 v[216:217], v[216:217], v[208:209]
	v_pk_mul_f32 v[218:219], v[218:219], v[210:211]
	v_lshlrev_b32_e32 v208, 16, v157
	v_lshlrev_b32_e32 v209, 16, v159
	v_lshlrev_b32_e32 v210, 16, v161
	v_lshlrev_b32_e32 v211, 16, v163
	v_pk_mul_f32 v[224:225], v[224:225], v[204:205]
	v_pk_mul_f32 v[226:227], v[226:227], v[206:207]
	v_pk_mul_f32 v[224:225], v[224:225], v[208:209]
	v_pk_mul_f32 v[226:227], v[226:227], v[210:211]
	v_and_b32_e32 v208, 0xffff0000, v157
	v_and_b32_e32 v209, 0xffff0000, v159
	v_and_b32_e32 v210, 0xffff0000, v161
	v_and_b32_e32 v211, 0xffff0000, v163
	v_pk_mul_f32 v[242:243], v[242:243], v[204:205]
	v_pk_mul_f32 v[244:245], v[244:245], v[206:207]
	v_pk_mul_f32 v[242:243], v[242:243], v[208:209]
	v_pk_mul_f32 v[244:245], v[244:245], v[210:211]
	v_cvt_pk_bf16_f32 v204, v212, v216
	v_cvt_pk_bf16_f32 v205, v224, v242
	v_cvt_pk_bf16_f32 v210, v213, v217
	v_cvt_pk_bf16_f32 v211, v225, v243
	v_cvt_pk_bf16_f32 v206, v214, v218
	v_cvt_pk_bf16_f32 v207, v226, v244
	v_cvt_pk_bf16_f32 v218, v215, v219
	v_cvt_pk_bf16_f32 v219, v227, v245
	v_and_b32_e32 v220, 1, v232
	v_mul_u32_u24_e32 v220, 0x7f8, v220
	v_add_u32_e32 v220, v21, v220
	s_mov_b32 vcc_lo, 0x55555555
	s_mov_b32 vcc_hi, 0x55555555
	v_cndmask_b32_dpp v208, v210, v204, vcc quad_perm:[1,0,3,2] row_mask:0xf bank_mask:0xf
	v_cndmask_b32_dpp v209, v211, v205, vcc quad_perm:[1,0,3,2] row_mask:0xf bank_mask:0xf
	v_cndmask_b32_dpp v216, v218, v206, vcc quad_perm:[1,0,3,2] row_mask:0xf bank_mask:0xf
	v_cndmask_b32_dpp v217, v219, v207, vcc quad_perm:[1,0,3,2] row_mask:0xf bank_mask:0xf
	s_not_b64 vcc, vcc
	v_cndmask_b32_dpp v210, v204, v210, vcc quad_perm:[1,0,3,2] row_mask:0xf bank_mask:0xf
	v_cndmask_b32_dpp v211, v205, v211, vcc quad_perm:[1,0,3,2] row_mask:0xf bank_mask:0xf
	v_cndmask_b32_dpp v218, v206, v218, vcc quad_perm:[1,0,3,2] row_mask:0xf bank_mask:0xf
	v_cndmask_b32_dpp v219, v207, v219, vcc quad_perm:[1,0,3,2] row_mask:0xf bank_mask:0xf
	global_store_dwordx4 v220, v[208:211], s[4:5]
	s_add_u32 s4, s10, 0x800
	s_addc_u32 s5, s11, 0
	s_add_u32 s4, s10, 0x1000
	s_addc_u32 s5, s11, 0
	global_store_dwordx4 v220, v[216:219], s[4:5]
	s_add_u32 s4, s10, 0x1800
	s_addc_u32 s5, s11, 0
	s_cbranch_execz .LBB0_607
